# phase 8 LN2 and sample in_proj A-tile build rewritten with hoisted loads; k/v f32 epilogue stores regrouped by permlane swaps into 64-byte runs
# speedup vs baseline: 1.0131x; 1.0012x over previous
.LBB0_186:
	v_mov_b32_e32 v1, v0
	s_waitcnt lgkmcnt(0)
	s_barrier
	s_and_b32 s6, s12, 7
	v_readfirstlane_b32 s15, v1
	s_ashr_i32 s7, s15, 6
	s_lshl_b32 s0, s7, 7
	s_ashr_i32 s1, s0, 31
	s_ashr_i32 s13, s12, 3
	s_lshl_b64 s[0:1], s[0:1], 1
	s_add_u32 s10, s8, s0
	s_addc_u32 s11, s9, s1
	s_lshl_b32 s16, s7, 1
	s_lshl_b32 s17, s6, 4
	s_add_i32 s2, s16, s17
	s_ashr_i32 s3, s2, 31
	v_readlane_b32 s36, v245, 2
	s_lshl_b64 s[0:1], s[2:3], 12
	v_readlane_b32 s38, v245, 4
	v_readlane_b32 s39, v245, 5
	s_add_u32 s0, s38, s0
	s_addc_u32 s1, s39, s1
	s_add_i32 s2, s2, 8
	s_mul_hi_i32 s3, s2, 0x6000
	s_mulk_i32 s2, 0x6000
	s_add_u32 s2, s70, s2
	s_addc_u32 s3, s71, s3
	v_and_b32_e32 v102, 63, v1
	s_add_u32 s4, s2, 0x1000
	s_addc_u32 s5, s3, 0
	s_waitcnt vmcnt(14)
	v_lshlrev_b32_e32 v118, 4, v102
	global_load_dwordx4 v[104:107], v118, s[4:5]
	global_load_dwordx4 v[108:111], v118, s[0:1]
	global_load_dwordx4 v[112:115], v118, s[2:3]
	s_mul_i32 s18, s13, 0x70
	v_and_b32_e32 v103, 15, v1
	s_waitcnt vmcnt(4)
	v_or_b32_e32 v2, s18, v103
	v_mov_b32_e32 v87, 0
	v_and_b32_e32 v86, 48, v1
	v_lshlrev_b32_e32 v119, 2, v102
	v_ashrrev_i32_e32 v3, 31, v2
	v_add_u32_e32 v4, 16, v2
	s_waitcnt vmcnt(3)
	v_add_u32_e32 v6, 32, v2
	v_add_u32_e32 v8, 48, v2
	v_add_u32_e32 v10, 64, v2
	v_add_u32_e32 v12, 0x50, v2
	v_add_u32_e32 v14, 0x60, v2
	v_or_b32_e32 v120, 0x100, v119
	v_lshlrev_b64 v[2:3], 11, v[2:3]
	v_ashrrev_i32_e32 v5, 31, v4
	v_ashrrev_i32_e32 v7, 31, v6
	v_ashrrev_i32_e32 v9, 31, v8
	v_ashrrev_i32_e32 v11, 31, v10
	v_ashrrev_i32_e32 v13, 31, v12
	v_ashrrev_i32_e32 v15, 31, v14
	v_lshl_add_u64 v[16:17], s[10:11], 0, v[86:87]
	v_lshlrev_b32_e32 v121, 2, v120
	v_lshlrev_b64 v[4:5], 11, v[4:5]
	v_lshlrev_b64 v[6:7], 11, v[6:7]
	v_lshlrev_b64 v[8:9], 11, v[8:9]
	v_lshlrev_b64 v[10:11], 11, v[10:11]
	v_lshlrev_b64 v[12:13], 11, v[12:13]
	v_lshlrev_b64 v[14:15], 11, v[14:15]
	v_lshl_add_u64 v[100:101], v[16:17], 0, v[2:3]
	v_lshl_add_u64 v[98:99], v[16:17], 0, v[4:5]
	v_lshl_add_u64 v[96:97], v[16:17], 0, v[6:7]
	v_lshl_add_u64 v[94:95], v[16:17], 0, v[8:9]
	v_lshl_add_u64 v[92:93], v[16:17], 0, v[10:11]
	v_lshl_add_u64 v[90:91], v[16:17], 0, v[12:13]
	v_lshl_add_u64 v[88:89], v[16:17], 0, v[14:15]
	global_load_dwordx4 v[46:49], v[100:101], off
	global_load_dwordx4 v[6:9], v[100:101], off offset:64
	global_load_dwordx4 v[50:53], v[96:97], off
	global_load_dwordx4 v[10:13], v[96:97], off offset:64
	global_load_dwordx4 v[54:57], v[92:93], off
	global_load_dwordx4 v[14:17], v[92:93], off offset:64
	global_load_dwordx4 v[58:61], v[88:89], off
	global_load_dwordx4 v[18:21], v[88:89], off offset:64
	global_load_dwordx4 v[74:77], v[98:99], off
	global_load_dwordx4 v[2:5], v[100:101], off offset:128
	global_load_dwordx4 v[62:65], v[98:99], off offset:64
	global_load_dwordx4 v[22:25], v[98:99], off offset:128
	global_load_dwordx4 v[78:81], v[94:95], off
	global_load_dwordx4 v[26:29], v[96:97], off offset:128
	global_load_dwordx4 v[66:69], v[94:95], off offset:64
	global_load_dwordx4 v[30:33], v[94:95], off offset:128
	global_load_dwordx4 v[82:85], v[90:91], off
	global_load_dwordx4 v[34:37], v[92:93], off offset:128
	global_load_dwordx4 v[70:73], v[90:91], off offset:64
	global_load_dwordx4 v[42:45], v[90:91], off offset:128
	global_load_dwordx4 v[38:41], v[88:89], off offset:128
	v_readlane_b32 s37, v245, 3
	v_readlane_b32 s40, v245, 6
	v_readlane_b32 s41, v245, 7
	v_readlane_b32 s42, v245, 8
	v_readlane_b32 s43, v245, 9
	v_readlane_b32 s44, v245, 10
	v_readlane_b32 s45, v245, 11
	v_readlane_b32 s46, v245, 12
	v_readlane_b32 s47, v245, 13
	v_readlane_b32 s48, v245, 14
	v_readlane_b32 s49, v245, 15
	v_readlane_b32 s50, v245, 16
	v_readlane_b32 s51, v245, 17
	global_load_dwordx4 v[122:125], v118, s[4:5] offset:1024
	global_load_dwordx4 v[126:129], v118, s[0:1] offset:1024
	global_load_dwordx4 v[130:133], v118, s[2:3] offset:1024
	global_load_dwordx4 v[134:137], v118, s[4:5] offset:2048
	global_load_dwordx4 v[138:141], v118, s[0:1] offset:2048
	global_load_dwordx4 v[142:145], v118, s[2:3] offset:2048
	global_load_dwordx4 v[146:149], v118, s[4:5] offset:3072
	global_load_dwordx4 v[150:153], v118, s[0:1] offset:3072
	global_load_dwordx4 v[154:157], v118, s[2:3] offset:3072
	s_add_u32 s0, s0, 0x1000
	s_addc_u32 s1, s1, 0
	s_add_u32 s2, s2, 0x6000
	s_addc_u32 s3, s3, 0
	s_add_u32 s4, s4, 0x6000
	s_addc_u32 s5, s5, 0
	global_load_dwordx4 v[176:179], v118, s[4:5]
	global_load_dwordx4 v[180:183], v118, s[0:1]
	global_load_dwordx4 v[184:187], v118, s[2:3]
	global_load_dwordx4 v[188:191], v118, s[4:5] offset:1024
	global_load_dwordx4 v[192:195], v118, s[0:1] offset:1024
	global_load_dwordx4 v[196:199], v118, s[2:3] offset:1024
	global_load_dwordx4 v[216:219], v118, s[4:5] offset:2048
	global_load_dwordx4 v[220:223], v118, s[0:1] offset:2048
	global_load_dwordx4 v[224:227], v118, s[2:3] offset:2048
	global_load_dwordx4 v[228:231], v118, s[4:5] offset:3072
	global_load_dwordx4 v[232:235], v118, s[0:1] offset:3072
	global_load_dwordx4 v[236:239], v118, s[2:3] offset:3072
	s_mul_i32 s11, s7, 0x1020
	s_add_i32 s10, 0, 0x18000
	s_add_i32 s11, s10, s11
	v_lshl_add_u32 v116, v102, 3, s11
	s_waitcnt vmcnt(42)
	v_add_f32_e32 v104, 1.0, v104
	v_add_f32_e32 v105, 1.0, v105
	v_add_f32_e32 v106, 1.0, v106
	v_add_f32_e32 v107, 1.0, v107
	v_fma_f32 v104, v108, v104, v112
	v_fma_f32 v105, v109, v105, v113
	v_fma_f32 v106, v110, v106, v114
	v_fma_f32 v107, v111, v107, v115
	v_cvt_pk_bf16_f32 v108, v104, v105
	v_cvt_pk_bf16_f32 v109, v106, v107
	ds_write_b64 v116, v[108:109]
	s_waitcnt vmcnt(18)
	v_add_f32_e32 v122, 1.0, v122
	v_add_f32_e32 v123, 1.0, v123
	v_add_f32_e32 v124, 1.0, v124
	v_add_f32_e32 v125, 1.0, v125
	v_fma_f32 v122, v126, v122, v130
	v_fma_f32 v123, v127, v123, v131
	v_fma_f32 v124, v128, v124, v132
	v_fma_f32 v125, v129, v125, v133
	v_cvt_pk_bf16_f32 v126, v122, v123
	v_cvt_pk_bf16_f32 v127, v124, v125
	ds_write_b64 v116, v[126:127] offset:512
	s_waitcnt vmcnt(15)
	v_add_f32_e32 v134, 1.0, v134
	v_add_f32_e32 v135, 1.0, v135
	v_add_f32_e32 v136, 1.0, v136
	v_add_f32_e32 v137, 1.0, v137
	v_fma_f32 v134, v138, v134, v142
	v_fma_f32 v135, v139, v135, v143
	v_fma_f32 v136, v140, v136, v144
	v_fma_f32 v137, v141, v137, v145
	v_cvt_pk_bf16_f32 v138, v134, v135
	v_cvt_pk_bf16_f32 v139, v136, v137
	ds_write_b64 v116, v[138:139] offset:1024
	s_waitcnt vmcnt(12)
	v_add_f32_e32 v146, 1.0, v146
	v_add_f32_e32 v147, 1.0, v147
	v_add_f32_e32 v148, 1.0, v148
	v_add_f32_e32 v149, 1.0, v149
	v_fma_f32 v146, v150, v146, v154
	v_fma_f32 v147, v151, v147, v155
	v_fma_f32 v148, v152, v148, v156
	v_fma_f32 v149, v153, v149, v157
	v_cvt_pk_bf16_f32 v150, v146, v147
	v_cvt_pk_bf16_f32 v151, v148, v149
	ds_write_b64 v116, v[150:151] offset:1536
	s_waitcnt vmcnt(9)
	v_add_f32_e32 v176, 1.0, v176
	v_add_f32_e32 v177, 1.0, v177
	v_add_f32_e32 v178, 1.0, v178
	v_add_f32_e32 v179, 1.0, v179
	v_fma_f32 v176, v180, v176, v184
	v_fma_f32 v177, v181, v177, v185
	v_fma_f32 v178, v182, v178, v186
	v_fma_f32 v179, v183, v179, v187
	v_cvt_pk_bf16_f32 v180, v176, v177
	v_cvt_pk_bf16_f32 v181, v178, v179
	ds_write_b64 v116, v[180:181] offset:2064
	s_waitcnt vmcnt(6)
	v_add_f32_e32 v188, 1.0, v188
	v_add_f32_e32 v189, 1.0, v189
	v_add_f32_e32 v190, 1.0, v190
	v_add_f32_e32 v191, 1.0, v191
	v_fma_f32 v188, v192, v188, v196
	v_fma_f32 v189, v193, v189, v197
	v_fma_f32 v190, v194, v190, v198
	v_fma_f32 v191, v195, v191, v199
	v_cvt_pk_bf16_f32 v192, v188, v189
	v_cvt_pk_bf16_f32 v193, v190, v191
	ds_write_b64 v116, v[192:193] offset:2576
	s_waitcnt vmcnt(3)
	v_add_f32_e32 v216, 1.0, v216
	v_add_f32_e32 v217, 1.0, v217
	v_add_f32_e32 v218, 1.0, v218
	v_add_f32_e32 v219, 1.0, v219
	v_fma_f32 v216, v220, v216, v224
	v_fma_f32 v217, v221, v217, v225
	v_fma_f32 v218, v222, v218, v226
	v_fma_f32 v219, v223, v219, v227
	v_cvt_pk_bf16_f32 v220, v216, v217
	v_cvt_pk_bf16_f32 v221, v218, v219
	ds_write_b64 v116, v[220:221] offset:3088
	s_waitcnt vmcnt(0)
	v_add_f32_e32 v228, 1.0, v228
	v_add_f32_e32 v229, 1.0, v229
	v_add_f32_e32 v230, 1.0, v230
	v_add_f32_e32 v231, 1.0, v231
	v_fma_f32 v228, v232, v228, v236
	v_fma_f32 v229, v233, v229, v237
	v_fma_f32 v230, v234, v230, v238
	v_fma_f32 v231, v235, v231, v239
	v_cvt_pk_bf16_f32 v232, v228, v229
	v_cvt_pk_bf16_f32 v233, v230, v231
	ds_write_b64 v116, v[232:233] offset:3600
	s_or_b32 s16, s16, 1
	s_mulk_i32 s16, 0x810
	s_add_i32 s11, s10, s16
	v_mov_b32_e32 v120, s10
	s_movk_i32 s0, 0x810
	s_nop 0
	v_mad_u32_u24 v120, v103, s0, v120
	s_lshl_b32 s0, s7, 8
	v_add3_u32 v86, v120, v86, s0
	s_mul_i32 s0, s7, 0x1c00
	s_cmp_gt_i32 s7, 6
	s_waitcnt lgkmcnt(0)
	s_barrier
	ds_read_b128 v[104:107], v86
	ds_read_b128 v[108:111], v86 offset:64
	s_waitcnt lgkmcnt(1)
	v_mfma_f32_16x16x32_bf16 v[46:49], v[46:49], v[104:107], 0
	v_mfma_f32_16x16x32_bf16 v[74:77], v[74:77], v[104:107], 0
	v_mfma_f32_16x16x32_bf16 v[50:53], v[50:53], v[104:107], 0
	v_mfma_f32_16x16x32_bf16 v[78:81], v[78:81], v[104:107], 0
	v_mfma_f32_16x16x32_bf16 v[58:61], v[58:61], v[104:107], 0
	v_mfma_f32_16x16x32_bf16 v[54:57], v[54:57], v[104:107], 0
	s_waitcnt lgkmcnt(0)
	v_mfma_f32_16x16x32_bf16 v[6:9], v[6:9], v[108:111], v[46:49]
	v_mfma_f32_16x16x32_bf16 v[46:49], v[62:65], v[108:111], v[74:77]
	v_mfma_f32_16x16x32_bf16 v[10:13], v[10:13], v[108:111], v[50:53]
	v_mfma_f32_16x16x32_bf16 v[50:53], v[66:69], v[108:111], v[78:81]
	v_mfma_f32_16x16x32_bf16 v[18:21], v[18:21], v[108:111], v[58:61]
	s_nop 2
	ds_read_b128 v[58:61], v86 offset:128
	ds_read_b128 v[62:65], v86 offset:192
	v_mfma_f32_16x16x32_bf16 v[14:17], v[14:17], v[108:111], v[54:57]
	s_waitcnt lgkmcnt(1)
	v_mfma_f32_16x16x32_bf16 v[2:5], v[2:5], v[58:61], v[6:9]
	v_mfma_f32_16x16x32_bf16 v[6:9], v[22:25], v[58:61], v[46:49]
	v_mfma_f32_16x16x32_bf16 v[22:25], v[30:33], v[58:61], v[50:53]
	global_load_dwordx4 v[30:33], v[100:101], off offset:192
	v_mfma_f32_16x16x32_bf16 v[14:17], v[34:37], v[58:61], v[14:17]
	global_load_dwordx4 v[34:37], v[98:99], off offset:192
	s_waitcnt vmcnt(1) lgkmcnt(0)
	v_mfma_f32_16x16x32_bf16 v[30:33], v[30:33], v[62:65], v[2:5]
	s_nop 2
	global_load_dwordx4 v[2:5], v[96:97], off offset:192
	s_waitcnt vmcnt(1)
	v_mfma_f32_16x16x32_bf16 v[6:9], v[34:37], v[62:65], v[6:9]
	global_load_dwordx4 v[34:37], v[94:95], off offset:192
	v_mfma_f32_16x16x32_bf16 v[10:13], v[26:29], v[58:61], v[10:13]
	s_waitcnt vmcnt(1)
	v_mfma_f32_16x16x32_bf16 v[10:13], v[2:5], v[62:65], v[10:13]
	global_load_dwordx4 v[2:5], v[92:93], off offset:192
	v_mfma_f32_16x16x32_bf16 v[18:21], v[38:41], v[58:61], v[18:21]
	global_load_dwordx4 v[38:41], v[88:89], off offset:192
	s_waitcnt vmcnt(2)
	v_mfma_f32_16x16x32_bf16 v[22:25], v[34:37], v[62:65], v[22:25]
	global_load_dwordx4 v[34:37], v[90:91], off offset:192
	v_mfma_f32_16x16x32_bf16 v[82:85], v[82:85], v[104:107], 0
	v_mfma_f32_16x16x32_bf16 v[54:57], v[70:73], v[108:111], v[82:85]
	v_mfma_f32_16x16x32_bf16 v[26:29], v[42:45], v[58:61], v[54:57]
	s_waitcnt vmcnt(2)
	v_mfma_f32_16x16x32_bf16 v[14:17], v[2:5], v[62:65], v[14:17]
	v_add_u32_e32 v2, 0, v118
	v_add_u32_e32 v3, s0, v2
	s_waitcnt vmcnt(0)
	v_mfma_f32_16x16x32_bf16 v[26:29], v[34:37], v[62:65], v[26:29]
	v_mfma_f32_16x16x32_bf16 v[18:21], v[38:41], v[62:65], v[18:21]
	ds_write_b128 v3, v[30:33]
	ds_write_b128 v3, v[6:9] offset:1024
	ds_write_b128 v3, v[10:13] offset:2048
	ds_write_b128 v3, v[22:25] offset:3072
	ds_write_b128 v3, v[14:17] offset:4096
	s_nop 1
	ds_write_b128 v3, v[26:29] offset:5120
	ds_write_b128 v3, v[18:21] offset:6144
	s_waitcnt lgkmcnt(0)
	s_barrier
	s_cbranch_scc1 .LBB0_195
	s_and_b32 s0, s15, 0xfffffc0
	s_lshl_b32 s0, s0, 4
	s_add_i32 s0, s0, 0
	v_lshl_add_u32 v3, v102, 4, s0
	v_lshl_add_u32 v24, s7, 10, v2
	ds_read_b128 v[4:7], v3
	ds_read_b128 v[8:11], v24 offset:7168
	ds_read_b128 v[12:15], v24 offset:14336
	ds_read_b128 v[16:19], v24 offset:35840
	ds_read_b128 v[20:23], v24 offset:21504
	s_mul_i32 s13, s13, 7
	s_add_i32 s0, s7, s13
	s_waitcnt lgkmcnt(3)
	v_pk_add_f32 v[8:9], v[4:5], v[8:9]
	ds_read_b128 v[2:5], v24 offset:28672
	v_pk_add_f32 v[6:7], v[6:7], v[10:11]
	s_waitcnt lgkmcnt(3)
	v_pk_add_f32 v[8:9], v[8:9], v[12:13]
	v_pk_add_f32 v[6:7], v[6:7], v[14:15]
	s_waitcnt lgkmcnt(1)
	v_pk_add_f32 v[8:9], v[8:9], v[20:21]
	v_pk_add_f32 v[6:7], v[6:7], v[22:23]
	s_waitcnt lgkmcnt(0)
	v_pk_add_f32 v[2:3], v[8:9], v[2:3]
	v_pk_add_f32 v[12:13], v[6:7], v[4:5]
	ds_read_b128 v[4:7], v24 offset:43008
	ds_read_b128 v[8:11], v24 offset:50176
	s_lshl_b32 s1, s0, 4
	v_pk_add_f32 v[12:13], v[12:13], v[18:19]
	s_ashr_i32 s7, s0, 5
	s_and_b32 s1, s1, 0x1f0
	v_bfe_u32 v1, v1, 4, 2
	v_pk_add_f32 v[2:3], v[2:3], v[16:17]
	s_waitcnt lgkmcnt(1)
	v_pk_add_f32 v[6:7], v[12:13], v[6:7]
	s_cmp_eq_u32 s7, 4
	v_pk_add_f32 v[2:3], v[2:3], v[4:5]
	s_waitcnt lgkmcnt(0)
	v_pk_add_f32 v[4:5], v[6:7], v[10:11]
	v_lshl_or_b32 v6, v1, 2, s1
	v_mov_b32_e32 v1, 0x3db504f3
	s_cselect_b64 vcc, -1, 0
	s_cmp_gt_u32 s0, 31
	v_cndmask_b32_e32 v1, 1.0, v1, vcc
	v_mov_b32_e32 v7, 0x3e38aa3b
	s_cselect_b64 vcc, -1, 0
	s_mul_i32 s0, s7, 0x1400000
	v_pk_add_f32 v[2:3], v[2:3], v[8:9]
	v_cndmask_b32_e32 v8, v7, v1, vcc
	s_mul_hi_i32 s1, s7, 0x1400000
	s_add_u32 s0, s54, s0
	v_pk_mul_f32 v[10:11], v[8:9], v[4:5] op_sel_hi:[0,1]
	v_pk_mul_f32 v[8:9], v[8:9], v[2:3] op_sel_hi:[0,1]
	s_addc_u32 s1, s55, s1
	s_lshl_b32 s2, s6, 13
	v_cvt_pk_bf16_f32 v12, v8, v9
	v_lshl_or_b32 v8, v103, 9, s2
	v_lshlrev_b32_e32 v86, 1, v8
	v_cvt_pk_bf16_f32 v13, v10, v11
	v_lshl_add_u64 v[10:11], s[0:1], 0, v[86:87]
	v_lshlrev_b32_e32 v86, 1, v6
	v_lshl_add_u64 v[10:11], v[10:11], 0, v[86:87]
	v_add_co_u32_e32 v10, vcc, 0x1000000, v10
	s_cmp_lt_i32 s7, 2
	s_nop 0
	v_addc_co_u32_e32 v11, vcc, 0, v11, vcc
	global_store_dwordx2 v[10:11], v[12:13], off
	s_cbranch_scc1 .LBB0_192
	s_mov_b64 s[4:5], 0
	s_cmp_eq_u32 s7, 2
	s_mov_b64 s[0:1], 0
	s_cbranch_scc0 .LBB0_190
	s_mov_b64 s[0:1], -1
	s_mov_b64 s[2:3], 0x82c4080
	s_and_b64 vcc, exec, s[4:5]
	s_cbranch_vccz .LBB0_193
	s_branch .LBB0_191

.LBB0_249:
	v_and_b32_e32 v230, 48, v0
	v_sub_u32_e32 v230, 0, v230
	v_ashrrev_i32_e32 v231, 31, v230
	s_add_u32 s58, s68, 0x80000
	s_addc_u32 s59, s69, 0
	s_add_u32 s62, s68, 0x2500000
	s_addc_u32 s63, s69, 0
	s_add_u32 s0, s68, 0x2540000
	s_addc_u32 s1, s69, 0
	v_writelane_b32 v245, s0, 36
	s_nop 1
	v_writelane_b32 v245, s1, 37
	s_add_u32 s0, s68, 0x2580000
	s_addc_u32 s1, s69, 0
	v_writelane_b32 v245, s0, 38
	s_nop 1
	v_writelane_b32 v245, s1, 39
	s_add_u32 s0, s68, 0x8c00000
	s_addc_u32 s1, s69, 0
	v_writelane_b32 v245, s0, 40
	s_nop 1
	v_writelane_b32 v245, s1, 41
	s_add_u32 s0, s68, 0xa000000
	s_addc_u32 s1, s69, 0
	v_writelane_b32 v245, s0, 42
	s_nop 1
	v_writelane_b32 v245, s1, 43
	s_add_u32 s0, s68, 0xb400000
	s_addc_u32 s1, s69, 0
	v_writelane_b32 v245, s0, 44
	s_nop 1
	v_writelane_b32 v245, s1, 45
	s_add_u32 s0, s68, 0xc800000
	s_addc_u32 s1, s69, 0
	s_add_u32 s56, s68, 0xdc00000
	s_addc_u32 s57, s69, 0
	v_writelane_b32 v245, s0, 46
	s_cmp_lt_i32 s92, 4
	s_nop 0
	v_writelane_b32 v245, s1, 47
	s_cselect_b64 s[0:1], -1, 0
	s_cmp_gt_i32 s93, 3
	s_cselect_b64 s[2:3], -1, 0
	s_and_b64 s[0:1], s[0:1], s[2:3]
	s_andn2_b64 vcc, exec, s[0:1]
	s_cbranch_vccnz .LBB0_508
	s_sub_i32 s15, s33, 32
	s_cmp_ge_i32 s12, s15
	s_mov_b64 s[0:1], -1
	s_cbranch_scc0 .LBB0_326
	s_sub_i32 s0, s12, s15
	s_and_b32 s0, s0, -8
	s_and_b32 s1, s12, 7
	s_or_b32 s0, s0, s1
	s_addk_i32 s0, 0x80
	s_mul_i32 s2, s15, 3
	s_ashr_i32 s3, s0, 31
	s_mul_hi_i32 s1, s15, 3
	s_add_u32 s0, s2, s0
	s_addc_u32 s1, s1, s3
	s_waitcnt vmcnt(1)
	v_mov_b64_e32 v[2:3], 0x37f
	s_waitcnt vmcnt(0)
	v_mov_b32_e32 v13, v0
	v_cmp_gt_i64_e32 vcc, s[0:1], v[2:3]
	s_nop 0
	v_readfirstlane_b32 s6, v13
	s_cbranch_vccnz .LBB0_325
	v_lshlrev_b32_e32 v1, 4, v13
	v_add_u32_e32 v2, 0x2000, v1
	v_ashrrev_i32_e32 v3, 31, v2
	v_lshrrev_b32_e32 v3, 22, v3
	v_add_u32_e32 v3, v2, v3
	v_ashrrev_i32_e32 v10, 10, v3
	v_mul_i32_i24_e32 v3, 0x400, v10
	v_sub_u32_e32 v2, v2, v3
	v_lshrrev_b32_e32 v3, 4, v2
	v_bitop3_b32 v2, v3, v2, 32 bitop3:0x6c
	v_ashrrev_i32_e32 v3, 31, v2
	v_lshrrev_b32_e32 v3, 26, v3
	v_add_u32_e32 v3, v2, v3
	v_lshlrev_b32_e32 v4, 3, v10
	v_ashrrev_i32_e32 v11, 6, v3
	v_and_b32_e32 v4, -16, v4
	v_add_u32_e32 v4, v11, v4
	v_and_b32_e32 v5, 3, v11
	s_mov_b32 s1, 0x1fffe0
	v_lshrrev_b32_e32 v6, 2, v4
	v_lshlrev_b32_e32 v7, 1, v4
	v_and_b32_e32 v3, 0xc0, v3
	v_and_or_b32 v5, v4, s1, v5
	v_and_b32_e32 v6, 4, v6
	v_and_b32_e32 v7, 24, v7
	v_sub_u32_e32 v2, v2, v3
	v_mov_b32_e32 v3, 1
	v_or3_b32 v5, v5, v6, v7
	v_lshlrev_b32_e32 v6, 5, v10
	v_ashrrev_i16_sdwa v2, v3, sext(v2) dst_sel:DWORD dst_unused:UNUSED_PAD src0_sel:DWORD src1_sel:BYTE_0
	v_and_b32_e32 v6, 32, v6
	v_bfe_i32 v12, v2, 0, 16
	v_add_lshl_u32 v2, v6, v12, 1
	v_lshl_add_u32 v130, v5, 11, v2
	v_lshl_add_u32 v132, v4, 11, v2
	v_bfe_i32 v2, v13, 27, 1
	v_lshrrev_b32_e32 v2, 22, v2
	v_add_u32_e32 v2, v1, v2
	v_and_b32_e32 v2, 0xfffffc00, v2
	v_sub_u32_e32 v1, v1, v2
	v_lshrrev_b32_e32 v2, 4, v1
	v_ashrrev_i32_e32 v4, 31, v13
	v_bitop3_b32 v1, v2, v1, 32 bitop3:0x6c
	v_lshrrev_b32_e32 v4, 26, v4
	v_ashrrev_i32_e32 v2, 31, v1
	v_add_u32_e32 v4, v13, v4
	v_lshrrev_b32_e32 v2, 26, v2
	v_ashrrev_i32_e32 v15, 6, v4
	v_add_u32_e32 v2, v1, v2
	v_lshlrev_b32_e32 v4, 3, v15
	v_ashrrev_i32_e32 v14, 6, v2
	v_and_b32_e32 v4, -16, v4
	v_add_u32_e32 v4, v14, v4
	v_and_b32_e32 v5, 3, v14
	v_and_or_b32 v5, v4, s1, v5
	s_ashr_i32 s1, s0, 31
	s_lshr_b32 s1, s1, 29
	s_add_i32 s1, s0, s1
	s_ashr_i32 s17, s6, 6
	s_ashr_i32 s2, s1, 3
	s_and_b32 s1, s1, -8
	s_mov_b64 s[38:39], s[62:63]
	s_ashr_i32 s18, s6, 8
	s_lshl_b32 s62, s17, 10
	s_sub_i32 s0, s0, s1
	s_cmp_lt_i32 s0, 0
	s_movk_i32 s1, 0x71
	s_cselect_b32 s1, s1, 0x70
	s_mul_i32 s0, s0, s1
	s_add_i32 s0, s0, s2
	s_mul_hi_i32 s1, s0, 0x92492493
	s_add_i32 s1, s1, s0
	s_lshr_b32 s2, s1, 31
	s_ashr_i32 s1, s1, 6
	s_add_i32 s1, s1, s2
	s_lshl_b32 s2, s1, 3
	v_and_b32_e32 v2, 0xc0, v2
	s_sub_i32 s3, 64, s2
	v_sub_u32_e32 v1, v1, v2
	s_min_i32 s3, s3, 8
	v_ashrrev_i16_sdwa v1, v3, sext(v1) dst_sel:DWORD dst_unused:UNUSED_PAD src0_sel:DWORD src1_sel:BYTE_0
	s_abs_i32 s4, s3
	v_bfe_i32 v16, v1, 0, 16
	v_cvt_f32_u32_e32 v1, s4
	s_sub_i32 s7, 0, s4
	s_mulk_i32 s1, 0x70
	s_sub_i32 s1, s0, s1
	v_rcp_iflag_f32_e32 v1, v1
	s_abs_i32 s5, s1
	s_xor_b32 s0, s1, s3
	s_ashr_i32 s0, s0, 31
	v_mul_f32_e32 v1, 0x4f7ffffe, v1
	v_cvt_u32_f32_e32 v1, v1
	v_lshrrev_b32_e32 v6, 2, v4
	v_lshlrev_b32_e32 v7, 1, v4
	v_and_b32_e32 v6, 4, v6
	v_readfirstlane_b32 s10, v1
	s_mul_i32 s7, s7, s10
	s_mul_hi_u32 s7, s10, s7
	s_add_i32 s10, s10, s7
	s_mul_hi_u32 s7, s5, s10
	s_mul_i32 s10, s7, s4
	s_sub_i32 s5, s5, s10
	s_add_i32 s10, s7, 1
	s_sub_i32 s11, s5, s4
	s_cmp_ge_u32 s5, s4
	s_cselect_b32 s7, s10, s7
	s_cselect_b32 s5, s11, s5
	s_add_i32 s10, s7, 1
	s_cmp_ge_u32 s5, s4
	s_cselect_b32 s4, s10, s7
	s_xor_b32 s4, s4, s0
	s_sub_i32 s0, s4, s0
	s_mul_i32 s3, s0, s3
	s_sub_i32 s1, s1, s3
	s_add_i32 s2, s2, s1
	v_and_b32_e32 v7, 24, v7
	s_ashr_i32 s3, s2, 31
	s_ashr_i32 s1, s0, 31
	v_or3_b32 v5, v5, v6, v7
	v_lshlrev_b32_e32 v6, 5, v15
	s_lshl_b64 s[74:75], s[2:3], 19
	s_lshl_b64 s[78:79], s[0:1], 19
	v_and_b32_e32 v6, 32, v6
	s_add_u32 s4, s8, s78
	v_add_lshl_u32 v2, v6, v16, 1
	s_addc_u32 s5, s9, s79
	s_add_i32 s1, s62, 0
	v_lshl_add_u32 v134, v5, 11, v2
	s_add_i32 m0, s1, 0x10000
	v_lshl_add_u32 v136, v4, 11, v2
	global_load_lds_dwordx4 v134, s[4:5]
	s_add_i32 m0, s1, 0x12000
	s_add_u32 s10, s4, 0x40000
	global_load_lds_dwordx4 v130, s[4:5]
	s_addc_u32 s11, s5, 0
	s_add_i32 m0, s1, 0x14000
	v_mov_b32_e32 v135, 0
	global_load_lds_dwordx4 v134, s[10:11]
	s_add_i32 m0, s1, 0x16000
	v_mov_b32_e32 v131, v135
	global_load_lds_dwordx4 v130, s[10:11]
	s_add_u32 s10, s52, s74
	s_addc_u32 s11, s53, s75
	s_add_i32 s7, s1, 0x2000
	s_mov_b32 m0, s1
	s_add_u32 s24, s10, 0x40000
	global_load_lds_dwordx4 v136, s[10:11]
	s_mov_b32 m0, s7
	s_addc_u32 s25, s11, 0
	s_add_i32 s13, s1, 0x4000
	global_load_lds_dwordx4 v132, s[10:11]
	s_mov_b32 m0, s13
	s_add_i32 s16, s1, 0x6000
	global_load_lds_dwordx4 v136, s[24:25]
	s_mov_b32 m0, s16
	v_mov_b32_e32 v137, v135
	global_load_lds_dwordx4 v132, s[24:25]
	v_mov_b32_e32 v133, v135
	s_mov_b64 s[36:37], s[84:85]
	v_lshl_add_u64 v[8:9], s[4:5], 0, v[134:135]
	v_lshl_add_u64 v[6:7], s[4:5], 0, v[130:131]
	v_lshl_add_u64 v[4:5], s[10:11], 0, v[136:137]
	s_cmp_lg_u32 s18, 1
	v_lshl_add_u64 v[2:3], s[10:11], 0, v[132:133]
	s_cbranch_scc1 .LBB0_254
	s_barrier

.LBB0_258:
	s_ashr_i32 s6, s0, 1
	s_lshl_b32 s1, s0, 8
	s_and_b32 s1, s1, 0x100
	s_mul_i32 s5, s6, 0x1400000
	s_mul_hi_i32 s4, s6, 0x1400000
	s_add_u32 s10, s54, s5
	s_addc_u32 s11, s55, s4
	s_cmp_eq_u32 s6, 4
	v_mov_b32_e32 v130, 0x3db504f3
	s_cselect_b64 vcc, -1, 0
	s_cmp_gt_u32 s0, 1
	v_cndmask_b32_e32 v130, 1.0, v130, vcc
	s_cselect_b64 vcc, -1, 0
	s_add_i32 s0, s6, -1
	s_cmp_lt_u32 s0, 2
	v_mov_b32_e32 v131, 0x3e38aa3b
	s_cselect_b64 s[4:5], -1, 0
	s_cmp_lt_i32 s2, 64
	v_cndmask_b32_e32 v140, v131, v130, vcc
	s_cselect_b64 vcc, -1, 0
	v_or_b32_e32 v130, s1, v143
	s_and_b64 s[0:1], vcc, exec
	s_mov_b32 s7, 0x4080000
	s_mov_b32 s1, 0x800000
	s_cselect_b32 s0, s7, 0x8284080
	s_cselect_b32 s1, s1, 0x10000
	s_cmp_eq_u32 s6, 2
	v_or_b32_e32 v131, s17, v130
	s_cselect_b32 s1, s1, 0
	v_readlane_b32 s16, v245, 18
	s_lshl_b32 s1, s1, 2
	v_readlane_b32 s30, v245, 32
	v_readlane_b32 s31, v245, 33
	s_add_u32 s1, s30, s1
	s_addc_u32 s7, s31, 0
	v_lshl_add_u32 v142, s2, 8, v142
	s_add_u32 s0, s1, s0
	v_mov_b32_e32 v139, 0
	v_lshlrev_b32_e32 v138, 1, v131
	v_add_u32_e32 v130, 0xffffc000, v142
	s_addc_u32 s1, s7, 0
	v_lshl_add_u64 v[146:147], s[10:11], 0, v[138:139]
	v_lshlrev_b32_e32 v138, 2, v131
	v_cndmask_b32_e32 v130, v130, v142, vcc
	v_lshl_add_u64 v[144:145], s[0:1], 0, v[138:139]
	s_movk_i32 s0, 0x80
	v_ashrrev_i32_e32 v143, 31, v142
	v_cmp_gt_i32_e64 s[0:1], s0, v130
	v_ashrrev_i32_e32 v131, 31, v130
	v_mov_b32_e32 v141, v140
	v_lshlrev_b64 v[132:133], 10, v[142:143]
	s_or_b64 s[0:1], vcc, s[0:1]
	v_lshlrev_b64 v[130:131], 11, v[130:131]
	v_lshl_add_u64 v[150:151], v[146:147], 0, v[132:133]
	s_and_b64 s[0:1], s[4:5], s[0:1]
	v_lshl_add_u64 v[148:149], v[144:145], 0, v[130:131]
	v_pk_mul_f32 v[132:133], v[140:141], v[128:129] op_sel_hi:[0,1]
	v_pk_mul_f32 v[130:131], v[140:141], v[126:127] op_sel_hi:[0,1]
	v_pk_mul_f32 v[136:137], v[140:141], v[96:97] op_sel_hi:[0,1]
	v_pk_mul_f32 v[134:135], v[140:141], v[94:95] op_sel_hi:[0,1]
	v_readlane_b32 s17, v245, 19
	v_readlane_b32 s18, v245, 20
	v_readlane_b32 s19, v245, 21
	v_readlane_b32 s20, v245, 22
	v_readlane_b32 s21, v245, 23
	v_readlane_b32 s22, v245, 24
	v_readlane_b32 s23, v245, 25
	v_readlane_b32 s24, v245, 26
	v_readlane_b32 s25, v245, 27
	v_readlane_b32 s26, v245, 28
	v_readlane_b32 s27, v245, 29
	v_readlane_b32 s28, v245, 30
	v_readlane_b32 s29, v245, 31
	v_cvt_pk_bf16_f32 v152, v130, v131
	v_cvt_pk_bf16_f32 v153, v132, v133
	v_cvt_pk_bf16_f32 v154, v134, v135
	v_cvt_pk_bf16_f32 v155, v136, v137
	global_store_dwordx4 v[150:151], v[152:155], off
	s_and_saveexec_b64 s[10:11], s[0:1]
	s_mov_b64 s[62:63], s[38:39]
	s_cbranch_execz .LBB0_260
	v_permlane16_swap_b32_e32 v130, v134
	v_permlane16_swap_b32_e32 v131, v135
	v_permlane16_swap_b32_e32 v132, v136
	v_permlane16_swap_b32_e32 v133, v137
	v_permlane32_swap_b32_e32 v130, v134
	v_permlane32_swap_b32_e32 v131, v135
	v_permlane32_swap_b32_e32 v132, v136
	v_permlane32_swap_b32_e32 v133, v137
	v_lshl_add_u64 v[232:233], v[148:149], 0, v[230:231]
	global_store_dwordx4 v[232:233], v[130:133], off nt
	global_store_dwordx4 v[232:233], v[134:137], off offset:64 nt
.LBB0_260:
	s_or_b64 exec, exec, s[10:11]
	v_mov_b32_e32 v152, v140
	v_mov_b32_e32 v153, v140
	v_pk_mul_f32 v[132:133], v[152:153], v[64:65]
	v_pk_mul_f32 v[130:131], v[140:141], v[62:63]
	v_pk_mul_f32 v[136:137], v[152:153], v[32:33]
	v_pk_mul_f32 v[134:135], v[140:141], v[30:31]
	v_cvt_pk_bf16_f32 v154, v130, v131
	v_cvt_pk_bf16_f32 v155, v132, v133
	s_nop 0
	v_cvt_pk_bf16_f32 v156, v134, v135
	v_cvt_pk_bf16_f32 v157, v136, v137
	global_store_dwordx4 v[150:151], v[154:157], off offset:256
	s_and_saveexec_b64 s[10:11], s[0:1]
	s_cbranch_execz .LBB0_262
	v_permlane16_swap_b32_e32 v130, v134
	v_permlane16_swap_b32_e32 v131, v135
	v_permlane16_swap_b32_e32 v132, v136
	v_permlane16_swap_b32_e32 v133, v137
	v_permlane32_swap_b32_e32 v130, v134
	v_permlane32_swap_b32_e32 v131, v135
	v_permlane32_swap_b32_e32 v132, v136
	v_permlane32_swap_b32_e32 v133, v137
	v_lshl_add_u64 v[232:233], v[148:149], 0, v[230:231]
	global_store_dwordx4 v[232:233], v[130:133], off offset:512 nt
	global_store_dwordx4 v[232:233], v[134:137], off offset:576 nt
.LBB0_262:
	s_or_b64 exec, exec, s[10:11]
	v_or_b32_e32 v130, 16, v142
	v_ashrrev_i32_e32 v131, 31, v130
	v_lshlrev_b64 v[132:133], 10, v[130:131]
	v_add_u32_e32 v131, 0xffffc010, v142
	v_cndmask_b32_e32 v130, v131, v130, vcc
	s_movk_i32 s0, 0x80
	v_cmp_gt_i32_e64 s[0:1], s0, v130
	v_ashrrev_i32_e32 v131, 31, v130
	s_or_b64 s[0:1], vcc, s[0:1]
	v_lshlrev_b64 v[130:131], 11, v[130:131]
	v_lshl_add_u64 v[150:151], v[146:147], 0, v[132:133]
	s_and_b64 s[0:1], s[4:5], s[0:1]
	v_lshl_add_u64 v[148:149], v[144:145], 0, v[130:131]
	v_pk_mul_f32 v[132:133], v[152:153], v[124:125]
	v_pk_mul_f32 v[130:131], v[140:141], v[122:123]
	v_pk_mul_f32 v[136:137], v[152:153], v[92:93]
	v_pk_mul_f32 v[134:135], v[140:141], v[90:91]
	v_cvt_pk_bf16_f32 v152, v130, v131
	v_cvt_pk_bf16_f32 v153, v132, v133
	s_nop 0
	v_cvt_pk_bf16_f32 v154, v134, v135
	v_cvt_pk_bf16_f32 v155, v136, v137
	global_store_dwordx4 v[150:151], v[152:155], off
	s_and_saveexec_b64 s[10:11], s[0:1]
	s_mov_b64 s[84:85], s[36:37]
	s_cbranch_execz .LBB0_264
	v_permlane16_swap_b32_e32 v130, v134
	v_permlane16_swap_b32_e32 v131, v135
	v_permlane16_swap_b32_e32 v132, v136
	v_permlane16_swap_b32_e32 v133, v137
	v_permlane32_swap_b32_e32 v130, v134
	v_permlane32_swap_b32_e32 v131, v135
	v_permlane32_swap_b32_e32 v132, v136
	v_permlane32_swap_b32_e32 v133, v137
	v_lshl_add_u64 v[232:233], v[148:149], 0, v[230:231]
	global_store_dwordx4 v[232:233], v[130:133], off nt
	global_store_dwordx4 v[232:233], v[134:137], off offset:64 nt
.LBB0_264:
	s_or_b64 exec, exec, s[10:11]
	v_mov_b32_e32 v152, v140
	v_mov_b32_e32 v153, v140
	v_pk_mul_f32 v[132:133], v[152:153], v[60:61]
	v_pk_mul_f32 v[130:131], v[140:141], v[58:59]
	v_pk_mul_f32 v[136:137], v[152:153], v[28:29]
	v_pk_mul_f32 v[134:135], v[140:141], v[26:27]
	v_cvt_pk_bf16_f32 v154, v130, v131
	v_cvt_pk_bf16_f32 v155, v132, v133
	s_nop 0
	v_cvt_pk_bf16_f32 v156, v134, v135
	v_cvt_pk_bf16_f32 v157, v136, v137
	global_store_dwordx4 v[150:151], v[154:157], off offset:256
	s_and_saveexec_b64 s[10:11], s[0:1]
	s_cbranch_execz .LBB0_266
	v_permlane16_swap_b32_e32 v130, v134
	v_permlane16_swap_b32_e32 v131, v135
	v_permlane16_swap_b32_e32 v132, v136
	v_permlane16_swap_b32_e32 v133, v137
	v_permlane32_swap_b32_e32 v130, v134
	v_permlane32_swap_b32_e32 v131, v135
	v_permlane32_swap_b32_e32 v132, v136
	v_permlane32_swap_b32_e32 v133, v137
	v_lshl_add_u64 v[232:233], v[148:149], 0, v[230:231]
	global_store_dwordx4 v[232:233], v[130:133], off offset:512 nt
	global_store_dwordx4 v[232:233], v[134:137], off offset:576 nt
.LBB0_266:
	s_or_b64 exec, exec, s[10:11]
	v_or_b32_e32 v130, 32, v142
	v_ashrrev_i32_e32 v131, 31, v130
	v_lshlrev_b64 v[132:133], 10, v[130:131]
	v_add_u32_e32 v131, 0xffffc020, v142
	v_cndmask_b32_e32 v130, v131, v130, vcc
	s_movk_i32 s0, 0x80
	v_cmp_gt_i32_e64 s[0:1], s0, v130
	v_ashrrev_i32_e32 v131, 31, v130
	s_or_b64 s[0:1], vcc, s[0:1]
	v_lshlrev_b64 v[130:131], 11, v[130:131]
	v_lshl_add_u64 v[150:151], v[146:147], 0, v[132:133]
	s_and_b64 s[0:1], s[4:5], s[0:1]
	v_lshl_add_u64 v[148:149], v[144:145], 0, v[130:131]
	v_pk_mul_f32 v[132:133], v[152:153], v[120:121]
	v_pk_mul_f32 v[130:131], v[140:141], v[118:119]
	v_pk_mul_f32 v[136:137], v[152:153], v[88:89]
	v_pk_mul_f32 v[134:135], v[140:141], v[86:87]
	v_cvt_pk_bf16_f32 v152, v130, v131
	v_cvt_pk_bf16_f32 v153, v132, v133
	s_nop 0
	v_cvt_pk_bf16_f32 v154, v134, v135
	v_cvt_pk_bf16_f32 v155, v136, v137
	global_store_dwordx4 v[150:151], v[152:155], off
	s_and_saveexec_b64 s[10:11], s[0:1]
	s_cbranch_execz .LBB0_268
	v_permlane16_swap_b32_e32 v130, v134
	v_permlane16_swap_b32_e32 v131, v135
	v_permlane16_swap_b32_e32 v132, v136
	v_permlane16_swap_b32_e32 v133, v137
	v_permlane32_swap_b32_e32 v130, v134
	v_permlane32_swap_b32_e32 v131, v135
	v_permlane32_swap_b32_e32 v132, v136
	v_permlane32_swap_b32_e32 v133, v137
	v_lshl_add_u64 v[232:233], v[148:149], 0, v[230:231]
	global_store_dwordx4 v[232:233], v[130:133], off nt
	global_store_dwordx4 v[232:233], v[134:137], off offset:64 nt
.LBB0_268:
	s_or_b64 exec, exec, s[10:11]
	v_mov_b32_e32 v152, v140
	v_mov_b32_e32 v153, v140
	v_pk_mul_f32 v[132:133], v[152:153], v[56:57]
	v_pk_mul_f32 v[130:131], v[140:141], v[54:55]
	v_pk_mul_f32 v[136:137], v[152:153], v[24:25]
	v_pk_mul_f32 v[134:135], v[140:141], v[22:23]
	v_cvt_pk_bf16_f32 v154, v130, v131
	v_cvt_pk_bf16_f32 v155, v132, v133
	s_nop 0
	v_cvt_pk_bf16_f32 v156, v134, v135
	v_cvt_pk_bf16_f32 v157, v136, v137
	global_store_dwordx4 v[150:151], v[154:157], off offset:256
	s_and_saveexec_b64 s[10:11], s[0:1]
	s_cbranch_execz .LBB0_270
	v_permlane16_swap_b32_e32 v130, v134
	v_permlane16_swap_b32_e32 v131, v135
	v_permlane16_swap_b32_e32 v132, v136
	v_permlane16_swap_b32_e32 v133, v137
	v_permlane32_swap_b32_e32 v130, v134
	v_permlane32_swap_b32_e32 v131, v135
	v_permlane32_swap_b32_e32 v132, v136
	v_permlane32_swap_b32_e32 v133, v137
	v_lshl_add_u64 v[232:233], v[148:149], 0, v[230:231]
	global_store_dwordx4 v[232:233], v[130:133], off offset:512 nt
	global_store_dwordx4 v[232:233], v[134:137], off offset:576 nt
.LBB0_270:
	s_or_b64 exec, exec, s[10:11]
	v_or_b32_e32 v130, 48, v142
	v_ashrrev_i32_e32 v131, 31, v130
	v_lshlrev_b64 v[132:133], 10, v[130:131]
	v_add_u32_e32 v131, 0xffffc030, v142
	v_cndmask_b32_e32 v130, v131, v130, vcc
	s_movk_i32 s0, 0x80
	v_cmp_gt_i32_e64 s[0:1], s0, v130
	v_ashrrev_i32_e32 v131, 31, v130
	s_or_b64 s[0:1], vcc, s[0:1]
	v_lshlrev_b64 v[130:131], 11, v[130:131]
	v_lshl_add_u64 v[150:151], v[146:147], 0, v[132:133]
	s_and_b64 s[0:1], s[4:5], s[0:1]
	v_lshl_add_u64 v[148:149], v[144:145], 0, v[130:131]
	v_pk_mul_f32 v[132:133], v[152:153], v[116:117]
	v_pk_mul_f32 v[130:131], v[140:141], v[114:115]
	v_pk_mul_f32 v[136:137], v[152:153], v[84:85]
	v_pk_mul_f32 v[134:135], v[140:141], v[82:83]
	v_cvt_pk_bf16_f32 v152, v130, v131
	v_cvt_pk_bf16_f32 v153, v132, v133
	s_nop 0
	v_cvt_pk_bf16_f32 v154, v134, v135
	v_cvt_pk_bf16_f32 v155, v136, v137
	global_store_dwordx4 v[150:151], v[152:155], off
	s_and_saveexec_b64 s[10:11], s[0:1]
	s_cbranch_execz .LBB0_272
	v_permlane16_swap_b32_e32 v130, v134
	v_permlane16_swap_b32_e32 v131, v135
	v_permlane16_swap_b32_e32 v132, v136
	v_permlane16_swap_b32_e32 v133, v137
	v_permlane32_swap_b32_e32 v130, v134
	v_permlane32_swap_b32_e32 v131, v135
	v_permlane32_swap_b32_e32 v132, v136
	v_permlane32_swap_b32_e32 v133, v137
	v_lshl_add_u64 v[232:233], v[148:149], 0, v[230:231]
	global_store_dwordx4 v[232:233], v[130:133], off nt
	global_store_dwordx4 v[232:233], v[134:137], off offset:64 nt
.LBB0_272:
	s_or_b64 exec, exec, s[10:11]
	v_mov_b32_e32 v152, v140
	v_mov_b32_e32 v153, v140
	v_pk_mul_f32 v[132:133], v[152:153], v[52:53]
	v_pk_mul_f32 v[130:131], v[140:141], v[50:51]
	v_pk_mul_f32 v[136:137], v[152:153], v[20:21]
	v_pk_mul_f32 v[134:135], v[140:141], v[18:19]
	v_cvt_pk_bf16_f32 v154, v130, v131
	v_cvt_pk_bf16_f32 v155, v132, v133
	s_nop 0
	v_cvt_pk_bf16_f32 v156, v134, v135
	v_cvt_pk_bf16_f32 v157, v136, v137
	global_store_dwordx4 v[150:151], v[154:157], off offset:256
	s_and_saveexec_b64 s[10:11], s[0:1]
	s_cbranch_execz .LBB0_274
	v_permlane16_swap_b32_e32 v130, v134
	v_permlane16_swap_b32_e32 v131, v135
	v_permlane16_swap_b32_e32 v132, v136
	v_permlane16_swap_b32_e32 v133, v137
	v_permlane32_swap_b32_e32 v130, v134
	v_permlane32_swap_b32_e32 v131, v135
	v_permlane32_swap_b32_e32 v132, v136
	v_permlane32_swap_b32_e32 v133, v137
	v_lshl_add_u64 v[232:233], v[148:149], 0, v[230:231]
	global_store_dwordx4 v[232:233], v[130:133], off offset:512 nt
	global_store_dwordx4 v[232:233], v[134:137], off offset:576 nt
.LBB0_274:
	s_or_b64 exec, exec, s[10:11]
	v_add_u32_e32 v130, 0x80, v142
	v_ashrrev_i32_e32 v131, 31, v130
	v_lshlrev_b64 v[132:133], 10, v[130:131]
	v_add_u32_e32 v131, 0xffffc080, v142
	s_movk_i32 s0, 0x80
	v_cndmask_b32_e32 v130, v131, v130, vcc
	v_cmp_gt_i32_e64 s[0:1], s0, v130
	v_ashrrev_i32_e32 v131, 31, v130
	s_or_b64 s[0:1], vcc, s[0:1]
	v_lshlrev_b64 v[130:131], 11, v[130:131]
	v_lshl_add_u64 v[150:151], v[146:147], 0, v[132:133]
	s_and_b64 s[0:1], s[4:5], s[0:1]
	v_lshl_add_u64 v[148:149], v[144:145], 0, v[130:131]
	v_pk_mul_f32 v[132:133], v[152:153], v[112:113]
	v_pk_mul_f32 v[130:131], v[140:141], v[110:111]
	v_pk_mul_f32 v[136:137], v[152:153], v[80:81]
	v_pk_mul_f32 v[134:135], v[140:141], v[78:79]
	v_cvt_pk_bf16_f32 v152, v130, v131
	v_cvt_pk_bf16_f32 v153, v132, v133
	s_nop 0
	v_cvt_pk_bf16_f32 v154, v134, v135
	v_cvt_pk_bf16_f32 v155, v136, v137
	global_store_dwordx4 v[150:151], v[152:155], off
	s_and_saveexec_b64 s[10:11], s[0:1]
	s_cbranch_execz .LBB0_276
	v_permlane16_swap_b32_e32 v130, v134
	v_permlane16_swap_b32_e32 v131, v135
	v_permlane16_swap_b32_e32 v132, v136
	v_permlane16_swap_b32_e32 v133, v137
	v_permlane32_swap_b32_e32 v130, v134
	v_permlane32_swap_b32_e32 v131, v135
	v_permlane32_swap_b32_e32 v132, v136
	v_permlane32_swap_b32_e32 v133, v137
	v_lshl_add_u64 v[232:233], v[148:149], 0, v[230:231]
	global_store_dwordx4 v[232:233], v[130:133], off nt
	global_store_dwordx4 v[232:233], v[134:137], off offset:64 nt
.LBB0_276:
	s_or_b64 exec, exec, s[10:11]
	v_mov_b32_e32 v152, v140
	v_mov_b32_e32 v153, v140
	v_pk_mul_f32 v[132:133], v[152:153], v[48:49]
	v_pk_mul_f32 v[130:131], v[140:141], v[46:47]
	v_pk_mul_f32 v[136:137], v[152:153], v[16:17]
	v_pk_mul_f32 v[134:135], v[140:141], v[14:15]
	v_cvt_pk_bf16_f32 v154, v130, v131
	v_cvt_pk_bf16_f32 v155, v132, v133
	s_nop 0
	v_cvt_pk_bf16_f32 v156, v134, v135
	v_cvt_pk_bf16_f32 v157, v136, v137
	global_store_dwordx4 v[150:151], v[154:157], off offset:256
	s_and_saveexec_b64 s[10:11], s[0:1]
	s_cbranch_execz .LBB0_278
	v_permlane16_swap_b32_e32 v130, v134
	v_permlane16_swap_b32_e32 v131, v135
	v_permlane16_swap_b32_e32 v132, v136
	v_permlane16_swap_b32_e32 v133, v137
	v_permlane32_swap_b32_e32 v130, v134
	v_permlane32_swap_b32_e32 v131, v135
	v_permlane32_swap_b32_e32 v132, v136
	v_permlane32_swap_b32_e32 v133, v137
	v_lshl_add_u64 v[232:233], v[148:149], 0, v[230:231]
	global_store_dwordx4 v[232:233], v[130:133], off offset:512 nt
	global_store_dwordx4 v[232:233], v[134:137], off offset:576 nt
.LBB0_278:
	s_or_b64 exec, exec, s[10:11]
	v_add_u32_e32 v130, 0x90, v142
	v_ashrrev_i32_e32 v131, 31, v130
	v_lshlrev_b64 v[132:133], 10, v[130:131]
	v_add_u32_e32 v131, 0xffffc090, v142
	v_cndmask_b32_e32 v130, v131, v130, vcc
	s_movk_i32 s0, 0x80
	v_cmp_gt_i32_e64 s[0:1], s0, v130
	v_ashrrev_i32_e32 v131, 31, v130
	s_or_b64 s[0:1], vcc, s[0:1]
	v_lshlrev_b64 v[130:131], 11, v[130:131]
	v_lshl_add_u64 v[150:151], v[146:147], 0, v[132:133]
	s_and_b64 s[0:1], s[4:5], s[0:1]
	v_lshl_add_u64 v[148:149], v[144:145], 0, v[130:131]
	v_pk_mul_f32 v[132:133], v[152:153], v[108:109]
	v_pk_mul_f32 v[130:131], v[140:141], v[106:107]
	v_pk_mul_f32 v[136:137], v[152:153], v[76:77]
	v_pk_mul_f32 v[134:135], v[140:141], v[74:75]
	v_cvt_pk_bf16_f32 v152, v130, v131
	v_cvt_pk_bf16_f32 v153, v132, v133
	s_nop 0
	v_cvt_pk_bf16_f32 v154, v134, v135
	v_cvt_pk_bf16_f32 v155, v136, v137
	global_store_dwordx4 v[150:151], v[152:155], off
	s_and_saveexec_b64 s[10:11], s[0:1]
	s_cbranch_execz .LBB0_280
	v_permlane16_swap_b32_e32 v130, v134
	v_permlane16_swap_b32_e32 v131, v135
	v_permlane16_swap_b32_e32 v132, v136
	v_permlane16_swap_b32_e32 v133, v137
	v_permlane32_swap_b32_e32 v130, v134
	v_permlane32_swap_b32_e32 v131, v135
	v_permlane32_swap_b32_e32 v132, v136
	v_permlane32_swap_b32_e32 v133, v137
	v_lshl_add_u64 v[232:233], v[148:149], 0, v[230:231]
	global_store_dwordx4 v[232:233], v[130:133], off nt
	global_store_dwordx4 v[232:233], v[134:137], off offset:64 nt
.LBB0_280:
	s_or_b64 exec, exec, s[10:11]
	v_mov_b32_e32 v152, v140
	v_mov_b32_e32 v153, v140
	v_pk_mul_f32 v[132:133], v[152:153], v[44:45]
	v_pk_mul_f32 v[130:131], v[140:141], v[42:43]
	v_pk_mul_f32 v[136:137], v[152:153], v[12:13]
	v_pk_mul_f32 v[134:135], v[140:141], v[10:11]
	v_cvt_pk_bf16_f32 v154, v130, v131
	v_cvt_pk_bf16_f32 v155, v132, v133
	s_nop 0
	v_cvt_pk_bf16_f32 v156, v134, v135
	v_cvt_pk_bf16_f32 v157, v136, v137
	global_store_dwordx4 v[150:151], v[154:157], off offset:256
	s_and_saveexec_b64 s[10:11], s[0:1]
	s_cbranch_execz .LBB0_282
	v_permlane16_swap_b32_e32 v130, v134
	v_permlane16_swap_b32_e32 v131, v135
	v_permlane16_swap_b32_e32 v132, v136
	v_permlane16_swap_b32_e32 v133, v137
	v_permlane32_swap_b32_e32 v130, v134
	v_permlane32_swap_b32_e32 v131, v135
	v_permlane32_swap_b32_e32 v132, v136
	v_permlane32_swap_b32_e32 v133, v137
	v_lshl_add_u64 v[232:233], v[148:149], 0, v[230:231]
	global_store_dwordx4 v[232:233], v[130:133], off offset:512 nt
	global_store_dwordx4 v[232:233], v[134:137], off offset:576 nt
.LBB0_282:
	s_or_b64 exec, exec, s[10:11]
	v_add_u32_e32 v130, 0xa0, v142
	v_ashrrev_i32_e32 v131, 31, v130
	v_lshlrev_b64 v[132:133], 10, v[130:131]
	v_add_u32_e32 v131, 0xffffc0a0, v142
	v_cndmask_b32_e32 v130, v131, v130, vcc
	s_movk_i32 s0, 0x80
	v_cmp_gt_i32_e64 s[0:1], s0, v130
	v_ashrrev_i32_e32 v131, 31, v130
	s_or_b64 s[0:1], vcc, s[0:1]
	v_lshlrev_b64 v[130:131], 11, v[130:131]
	v_lshl_add_u64 v[150:151], v[146:147], 0, v[132:133]
	s_and_b64 s[0:1], s[4:5], s[0:1]
	v_lshl_add_u64 v[148:149], v[144:145], 0, v[130:131]
	v_pk_mul_f32 v[132:133], v[152:153], v[104:105]
	v_pk_mul_f32 v[130:131], v[140:141], v[102:103]
	v_pk_mul_f32 v[136:137], v[152:153], v[72:73]
	v_pk_mul_f32 v[134:135], v[140:141], v[70:71]
	v_cvt_pk_bf16_f32 v152, v130, v131
	v_cvt_pk_bf16_f32 v153, v132, v133
	s_nop 0
	v_cvt_pk_bf16_f32 v154, v134, v135
	v_cvt_pk_bf16_f32 v155, v136, v137
	global_store_dwordx4 v[150:151], v[152:155], off
	s_and_saveexec_b64 s[10:11], s[0:1]
	s_cbranch_execz .LBB0_284
	v_permlane16_swap_b32_e32 v130, v134
	v_permlane16_swap_b32_e32 v131, v135
	v_permlane16_swap_b32_e32 v132, v136
	v_permlane16_swap_b32_e32 v133, v137
	v_permlane32_swap_b32_e32 v130, v134
	v_permlane32_swap_b32_e32 v131, v135
	v_permlane32_swap_b32_e32 v132, v136
	v_permlane32_swap_b32_e32 v133, v137
	v_lshl_add_u64 v[232:233], v[148:149], 0, v[230:231]
	global_store_dwordx4 v[232:233], v[130:133], off nt
	global_store_dwordx4 v[232:233], v[134:137], off offset:64 nt
.LBB0_284:
	s_or_b64 exec, exec, s[10:11]
	v_mov_b32_e32 v152, v140
	v_mov_b32_e32 v153, v140
	v_pk_mul_f32 v[132:133], v[152:153], v[40:41]
	v_pk_mul_f32 v[130:131], v[140:141], v[38:39]
	v_pk_mul_f32 v[136:137], v[152:153], v[8:9]
	v_pk_mul_f32 v[134:135], v[140:141], v[6:7]
	v_cvt_pk_bf16_f32 v154, v130, v131
	v_cvt_pk_bf16_f32 v155, v132, v133
	s_nop 0
	v_cvt_pk_bf16_f32 v156, v134, v135
	v_cvt_pk_bf16_f32 v157, v136, v137
	global_store_dwordx4 v[150:151], v[154:157], off offset:256
	s_and_saveexec_b64 s[10:11], s[0:1]
	s_cbranch_execz .LBB0_286
	v_permlane16_swap_b32_e32 v130, v134
	v_permlane16_swap_b32_e32 v131, v135
	v_permlane16_swap_b32_e32 v132, v136
	v_permlane16_swap_b32_e32 v133, v137
	v_permlane32_swap_b32_e32 v130, v134
	v_permlane32_swap_b32_e32 v131, v135
	v_permlane32_swap_b32_e32 v132, v136
	v_permlane32_swap_b32_e32 v133, v137
	v_lshl_add_u64 v[232:233], v[148:149], 0, v[230:231]
	global_store_dwordx4 v[232:233], v[130:133], off offset:512 nt
	global_store_dwordx4 v[232:233], v[134:137], off offset:576 nt
.LBB0_286:
	s_or_b64 exec, exec, s[10:11]
	v_add_u32_e32 v130, 0xb0, v142
	v_ashrrev_i32_e32 v131, 31, v130
	v_lshlrev_b64 v[132:133], 10, v[130:131]
	v_add_u32_e32 v131, 0xffffc0b0, v142
	v_cndmask_b32_e32 v130, v131, v130, vcc
	s_movk_i32 s0, 0x80
	v_cmp_gt_i32_e64 s[0:1], s0, v130
	v_ashrrev_i32_e32 v131, 31, v130
	s_or_b64 s[0:1], vcc, s[0:1]
	v_lshlrev_b64 v[130:131], 11, v[130:131]
	v_lshl_add_u64 v[146:147], v[146:147], 0, v[132:133]
	s_and_b64 s[0:1], s[4:5], s[0:1]
	v_lshl_add_u64 v[142:143], v[144:145], 0, v[130:131]
	v_pk_mul_f32 v[132:133], v[152:153], v[100:101]
	v_pk_mul_f32 v[130:131], v[140:141], v[98:99]
	v_pk_mul_f32 v[136:137], v[152:153], v[68:69]
	v_pk_mul_f32 v[134:135], v[140:141], v[66:67]
	v_cvt_pk_bf16_f32 v148, v130, v131
	v_cvt_pk_bf16_f32 v149, v132, v133
	s_nop 0
	v_cvt_pk_bf16_f32 v150, v134, v135
	v_cvt_pk_bf16_f32 v151, v136, v137
	global_store_dwordx4 v[146:147], v[148:151], off
	s_and_saveexec_b64 s[4:5], s[0:1]
	s_cbranch_execz .LBB0_288
	v_permlane16_swap_b32_e32 v130, v134
	v_permlane16_swap_b32_e32 v131, v135
	v_permlane16_swap_b32_e32 v132, v136
	v_permlane16_swap_b32_e32 v133, v137
	v_permlane32_swap_b32_e32 v130, v134
	v_permlane32_swap_b32_e32 v131, v135
	v_permlane32_swap_b32_e32 v132, v136
	v_permlane32_swap_b32_e32 v133, v137
	v_lshl_add_u64 v[232:233], v[142:143], 0, v[230:231]
	global_store_dwordx4 v[232:233], v[130:133], off nt
	global_store_dwordx4 v[232:233], v[134:137], off offset:64 nt
.LBB0_288:
	s_or_b64 exec, exec, s[4:5]
	s_nop 0
	v_mov_b32_e32 v134, v140
	v_mov_b32_e32 v135, v140
	v_pk_mul_f32 v[132:133], v[134:135], v[36:37]
	v_pk_mul_f32 v[130:131], v[140:141], v[34:35]
	v_pk_mul_f32 v[136:137], v[134:135], v[4:5]
	v_pk_mul_f32 v[134:135], v[140:141], v[2:3]
	v_cvt_pk_bf16_f32 v148, v130, v131
	v_cvt_pk_bf16_f32 v149, v132, v133
	s_nop 0
	v_cvt_pk_bf16_f32 v150, v134, v135
	v_cvt_pk_bf16_f32 v151, v136, v137
	global_store_dwordx4 v[146:147], v[148:151], off offset:256
	s_and_saveexec_b64 s[4:5], s[0:1]
	s_cbranch_execz .LBB0_290
	v_permlane16_swap_b32_e32 v130, v134
	v_permlane16_swap_b32_e32 v131, v135
	v_permlane16_swap_b32_e32 v132, v136
	v_permlane16_swap_b32_e32 v133, v137
	v_permlane32_swap_b32_e32 v130, v134
	v_permlane32_swap_b32_e32 v131, v135
	v_permlane32_swap_b32_e32 v132, v136
	v_permlane32_swap_b32_e32 v133, v137
	v_lshl_add_u64 v[232:233], v[142:143], 0, v[230:231]
	global_store_dwordx4 v[232:233], v[130:133], off offset:512 nt
	global_store_dwordx4 v[232:233], v[134:137], off offset:576 nt

.LBB0_342:
	s_ashr_i32 s5, s0, 1
	s_lshl_b32 s1, s0, 8
	s_and_b32 s1, s1, 0x100
	s_mul_i32 s18, s5, 0x1400000
	s_mul_hi_i32 s17, s5, 0x1400000
	s_add_u32 s18, s54, s18
	s_addc_u32 s19, s55, s17
	s_cmp_eq_u32 s5, 4
	s_cselect_b64 vcc, -1, 0
	s_cmp_gt_u32 s0, 1
	v_cndmask_b32_e32 v130, 1.0, v173, vcc
	s_cselect_b64 vcc, -1, 0
	s_add_i32 s0, s5, -1
	s_cmp_lt_u32 s0, 2
	s_cselect_b64 s[84:85], -1, 0
	s_cmp_lt_i32 s4, 64
	v_cndmask_b32_e32 v154, v174, v130, vcc
	s_cselect_b64 vcc, -1, 0
	v_or_b32_e32 v131, s1, v169
	s_and_b64 s[0:1], vcc, exec
	s_mov_b32 s0, 0x4080000
	s_mov_b32 s1, 0x800000
	s_cselect_b32 s0, s0, 0x8284080
	s_cselect_b32 s1, s1, 0x10000
	s_cmp_eq_u32 s5, 2
	s_cselect_b32 s1, s1, 0
	v_readlane_b32 s36, v245, 18
	s_lshl_b32 s1, s1, 2
	v_readlane_b32 s50, v245, 32
	v_readlane_b32 s51, v245, 33
	s_add_u32 s1, s50, s1
	v_lshl_add_u32 v156, s4, 8, v1
	s_addc_u32 s17, s51, 0
	v_add_u32_e32 v130, 0xffffc000, v156
	s_add_u32 s0, s1, s0
	v_lshlrev_b32_e32 v146, 1, v131
	v_cndmask_b32_e32 v130, v130, v156, vcc
	s_addc_u32 s1, s17, 0
	v_lshl_add_u64 v[160:161], s[18:19], 0, v[146:147]
	v_lshlrev_b32_e32 v146, 2, v131
	v_lshl_add_u64 v[158:159], s[0:1], 0, v[146:147]
	v_ashrrev_i32_e32 v157, 31, v156
	v_cmp_gt_i32_e64 s[0:1], s77, v130
	v_ashrrev_i32_e32 v131, 31, v130
	v_lshlrev_b64 v[132:133], 10, v[156:157]
	s_or_b64 s[0:1], vcc, s[0:1]
	v_lshlrev_b64 v[130:131], 11, v[130:131]
	v_lshl_add_u64 v[164:165], v[160:161], 0, v[132:133]
	s_and_b64 s[0:1], s[84:85], s[0:1]
	v_lshl_add_u64 v[162:163], v[158:159], 0, v[130:131]
	v_pk_mul_f32 v[132:133], v[154:155], v[128:129] op_sel_hi:[0,1]
	v_pk_mul_f32 v[130:131], v[154:155], v[126:127] op_sel_hi:[0,1]
	v_pk_mul_f32 v[136:137], v[154:155], v[96:97] op_sel_hi:[0,1]
	v_pk_mul_f32 v[134:135], v[154:155], v[94:95] op_sel_hi:[0,1]
	v_readlane_b32 s37, v245, 19
	v_readlane_b32 s38, v245, 20
	v_readlane_b32 s39, v245, 21
	v_readlane_b32 s40, v245, 22
	v_readlane_b32 s41, v245, 23
	v_readlane_b32 s42, v245, 24
	v_readlane_b32 s43, v245, 25
	v_readlane_b32 s44, v245, 26
	v_readlane_b32 s45, v245, 27
	v_readlane_b32 s46, v245, 28
	v_readlane_b32 s47, v245, 29
	v_readlane_b32 s48, v245, 30
	v_readlane_b32 s49, v245, 31
	v_cvt_pk_bf16_f32 v176, v130, v131
	v_cvt_pk_bf16_f32 v177, v132, v133
	v_cvt_pk_bf16_f32 v178, v134, v135
	v_cvt_pk_bf16_f32 v179, v136, v137
	global_store_dwordx4 v[164:165], v[176:179], off
	s_and_saveexec_b64 s[72:73], s[0:1]
	s_cbranch_execz .LBB0_344
	v_permlane16_swap_b32_e32 v130, v134
	v_permlane16_swap_b32_e32 v131, v135
	v_permlane16_swap_b32_e32 v132, v136
	v_permlane16_swap_b32_e32 v133, v137
	v_permlane32_swap_b32_e32 v130, v134
	v_permlane32_swap_b32_e32 v131, v135
	v_permlane32_swap_b32_e32 v132, v136
	v_permlane32_swap_b32_e32 v133, v137
	v_lshl_add_u64 v[232:233], v[162:163], 0, v[230:231]
	global_store_dwordx4 v[232:233], v[130:133], off nt
	global_store_dwordx4 v[232:233], v[134:137], off offset:64 nt
.LBB0_344:
	s_or_b64 exec, exec, s[72:73]
	v_mov_b32_e32 v155, v154
	v_mov_b32_e32 v166, v154
	v_mov_b32_e32 v167, v154
	v_pk_mul_f32 v[132:133], v[166:167], v[64:65]
	v_pk_mul_f32 v[130:131], v[154:155], v[62:63]
	v_pk_mul_f32 v[136:137], v[166:167], v[32:33]
	v_pk_mul_f32 v[134:135], v[154:155], v[30:31]
	v_cvt_pk_bf16_f32 v176, v130, v131
	v_cvt_pk_bf16_f32 v177, v132, v133
	s_nop 0
	v_cvt_pk_bf16_f32 v178, v134, v135
	v_cvt_pk_bf16_f32 v179, v136, v137
	global_store_dwordx4 v[164:165], v[176:179], off offset:256
	s_and_saveexec_b64 s[72:73], s[0:1]
	s_cbranch_execz .LBB0_346
	v_permlane16_swap_b32_e32 v130, v134
	v_permlane16_swap_b32_e32 v131, v135
	v_permlane16_swap_b32_e32 v132, v136
	v_permlane16_swap_b32_e32 v133, v137
	v_permlane32_swap_b32_e32 v130, v134
	v_permlane32_swap_b32_e32 v131, v135
	v_permlane32_swap_b32_e32 v132, v136
	v_permlane32_swap_b32_e32 v133, v137
	v_lshl_add_u64 v[232:233], v[162:163], 0, v[230:231]
	global_store_dwordx4 v[232:233], v[130:133], off offset:512 nt
	global_store_dwordx4 v[232:233], v[134:137], off offset:576 nt
.LBB0_346:
	s_or_b64 exec, exec, s[72:73]
	v_or_b32_e32 v130, 16, v156
	v_ashrrev_i32_e32 v131, 31, v130
	v_lshlrev_b64 v[132:133], 10, v[130:131]
	v_add_u32_e32 v131, 0xffffc010, v156
	v_cndmask_b32_e32 v130, v131, v130, vcc
	v_cmp_gt_i32_e64 s[0:1], s77, v130
	v_ashrrev_i32_e32 v131, 31, v130
	s_or_b64 s[0:1], vcc, s[0:1]
	v_lshlrev_b64 v[130:131], 11, v[130:131]
	v_lshl_add_u64 v[164:165], v[160:161], 0, v[132:133]
	s_and_b64 s[0:1], s[84:85], s[0:1]
	v_lshl_add_u64 v[162:163], v[158:159], 0, v[130:131]
	v_pk_mul_f32 v[132:133], v[166:167], v[124:125]
	v_pk_mul_f32 v[130:131], v[154:155], v[122:123]
	v_pk_mul_f32 v[136:137], v[166:167], v[92:93]
	v_pk_mul_f32 v[134:135], v[154:155], v[90:91]
	v_cvt_pk_bf16_f32 v176, v130, v131
	v_cvt_pk_bf16_f32 v177, v132, v133
	s_nop 0
	v_cvt_pk_bf16_f32 v178, v134, v135
	v_cvt_pk_bf16_f32 v179, v136, v137
	global_store_dwordx4 v[164:165], v[176:179], off
	s_and_saveexec_b64 s[72:73], s[0:1]
	s_cbranch_execz .LBB0_348
	v_permlane16_swap_b32_e32 v130, v134
	v_permlane16_swap_b32_e32 v131, v135
	v_permlane16_swap_b32_e32 v132, v136
	v_permlane16_swap_b32_e32 v133, v137
	v_permlane32_swap_b32_e32 v130, v134
	v_permlane32_swap_b32_e32 v131, v135
	v_permlane32_swap_b32_e32 v132, v136
	v_permlane32_swap_b32_e32 v133, v137
	v_lshl_add_u64 v[232:233], v[162:163], 0, v[230:231]
	global_store_dwordx4 v[232:233], v[130:133], off nt
	global_store_dwordx4 v[232:233], v[134:137], off offset:64 nt
.LBB0_348:
	s_or_b64 exec, exec, s[72:73]
	v_mov_b32_e32 v166, v154
	v_mov_b32_e32 v167, v154
	v_pk_mul_f32 v[132:133], v[166:167], v[60:61]
	v_pk_mul_f32 v[130:131], v[154:155], v[58:59]
	v_pk_mul_f32 v[136:137], v[166:167], v[28:29]
	v_pk_mul_f32 v[134:135], v[154:155], v[26:27]
	v_cvt_pk_bf16_f32 v176, v130, v131
	v_cvt_pk_bf16_f32 v177, v132, v133
	s_nop 0
	v_cvt_pk_bf16_f32 v178, v134, v135
	v_cvt_pk_bf16_f32 v179, v136, v137
	global_store_dwordx4 v[164:165], v[176:179], off offset:256
	s_and_saveexec_b64 s[72:73], s[0:1]
	s_cbranch_execz .LBB0_350
	v_permlane16_swap_b32_e32 v130, v134
	v_permlane16_swap_b32_e32 v131, v135
	v_permlane16_swap_b32_e32 v132, v136
	v_permlane16_swap_b32_e32 v133, v137
	v_permlane32_swap_b32_e32 v130, v134
	v_permlane32_swap_b32_e32 v131, v135
	v_permlane32_swap_b32_e32 v132, v136
	v_permlane32_swap_b32_e32 v133, v137
	v_lshl_add_u64 v[232:233], v[162:163], 0, v[230:231]
	global_store_dwordx4 v[232:233], v[130:133], off offset:512 nt
	global_store_dwordx4 v[232:233], v[134:137], off offset:576 nt
.LBB0_350:
	s_or_b64 exec, exec, s[72:73]
	v_or_b32_e32 v130, 32, v156
	v_ashrrev_i32_e32 v131, 31, v130
	v_lshlrev_b64 v[132:133], 10, v[130:131]
	v_add_u32_e32 v131, 0xffffc020, v156
	v_cndmask_b32_e32 v130, v131, v130, vcc
	v_cmp_gt_i32_e64 s[0:1], s77, v130
	v_ashrrev_i32_e32 v131, 31, v130
	s_or_b64 s[0:1], vcc, s[0:1]
	v_lshlrev_b64 v[130:131], 11, v[130:131]
	v_lshl_add_u64 v[164:165], v[160:161], 0, v[132:133]
	s_and_b64 s[0:1], s[84:85], s[0:1]
	v_lshl_add_u64 v[162:163], v[158:159], 0, v[130:131]
	v_pk_mul_f32 v[132:133], v[166:167], v[120:121]
	v_pk_mul_f32 v[130:131], v[154:155], v[118:119]
	v_pk_mul_f32 v[136:137], v[166:167], v[88:89]
	v_pk_mul_f32 v[134:135], v[154:155], v[86:87]
	v_cvt_pk_bf16_f32 v176, v130, v131
	v_cvt_pk_bf16_f32 v177, v132, v133
	s_nop 0
	v_cvt_pk_bf16_f32 v178, v134, v135
	v_cvt_pk_bf16_f32 v179, v136, v137
	global_store_dwordx4 v[164:165], v[176:179], off
	s_and_saveexec_b64 s[72:73], s[0:1]
	s_cbranch_execz .LBB0_352
	v_permlane16_swap_b32_e32 v130, v134
	v_permlane16_swap_b32_e32 v131, v135
	v_permlane16_swap_b32_e32 v132, v136
	v_permlane16_swap_b32_e32 v133, v137
	v_permlane32_swap_b32_e32 v130, v134
	v_permlane32_swap_b32_e32 v131, v135
	v_permlane32_swap_b32_e32 v132, v136
	v_permlane32_swap_b32_e32 v133, v137
	v_lshl_add_u64 v[232:233], v[162:163], 0, v[230:231]
	global_store_dwordx4 v[232:233], v[130:133], off nt
	global_store_dwordx4 v[232:233], v[134:137], off offset:64 nt
.LBB0_352:
	s_or_b64 exec, exec, s[72:73]
	v_mov_b32_e32 v166, v154
	v_mov_b32_e32 v167, v154
	v_pk_mul_f32 v[132:133], v[166:167], v[56:57]
	v_pk_mul_f32 v[130:131], v[154:155], v[54:55]
	v_pk_mul_f32 v[136:137], v[166:167], v[24:25]
	v_pk_mul_f32 v[134:135], v[154:155], v[22:23]
	v_cvt_pk_bf16_f32 v176, v130, v131
	v_cvt_pk_bf16_f32 v177, v132, v133
	s_nop 0
	v_cvt_pk_bf16_f32 v178, v134, v135
	v_cvt_pk_bf16_f32 v179, v136, v137
	global_store_dwordx4 v[164:165], v[176:179], off offset:256
	s_and_saveexec_b64 s[72:73], s[0:1]
	s_cbranch_execz .LBB0_354
	v_permlane16_swap_b32_e32 v130, v134
	v_permlane16_swap_b32_e32 v131, v135
	v_permlane16_swap_b32_e32 v132, v136
	v_permlane16_swap_b32_e32 v133, v137
	v_permlane32_swap_b32_e32 v130, v134
	v_permlane32_swap_b32_e32 v131, v135
	v_permlane32_swap_b32_e32 v132, v136
	v_permlane32_swap_b32_e32 v133, v137
	v_lshl_add_u64 v[232:233], v[162:163], 0, v[230:231]
	global_store_dwordx4 v[232:233], v[130:133], off offset:512 nt
	global_store_dwordx4 v[232:233], v[134:137], off offset:576 nt
.LBB0_354:
	s_or_b64 exec, exec, s[72:73]
	v_or_b32_e32 v130, 48, v156
	v_ashrrev_i32_e32 v131, 31, v130
	v_lshlrev_b64 v[132:133], 10, v[130:131]
	v_add_u32_e32 v131, 0xffffc030, v156
	v_cndmask_b32_e32 v130, v131, v130, vcc
	v_cmp_gt_i32_e64 s[0:1], s77, v130
	v_ashrrev_i32_e32 v131, 31, v130
	s_or_b64 s[0:1], vcc, s[0:1]
	v_lshlrev_b64 v[130:131], 11, v[130:131]
	v_lshl_add_u64 v[164:165], v[160:161], 0, v[132:133]
	s_and_b64 s[0:1], s[84:85], s[0:1]
	v_lshl_add_u64 v[162:163], v[158:159], 0, v[130:131]
	v_pk_mul_f32 v[132:133], v[166:167], v[116:117]
	v_pk_mul_f32 v[130:131], v[154:155], v[114:115]
	v_pk_mul_f32 v[136:137], v[166:167], v[84:85]
	v_pk_mul_f32 v[134:135], v[154:155], v[82:83]
	v_cvt_pk_bf16_f32 v176, v130, v131
	v_cvt_pk_bf16_f32 v177, v132, v133
	s_nop 0
	v_cvt_pk_bf16_f32 v178, v134, v135
	v_cvt_pk_bf16_f32 v179, v136, v137
	global_store_dwordx4 v[164:165], v[176:179], off
	s_and_saveexec_b64 s[72:73], s[0:1]
	s_cbranch_execz .LBB0_356
	v_permlane16_swap_b32_e32 v130, v134
	v_permlane16_swap_b32_e32 v131, v135
	v_permlane16_swap_b32_e32 v132, v136
	v_permlane16_swap_b32_e32 v133, v137
	v_permlane32_swap_b32_e32 v130, v134
	v_permlane32_swap_b32_e32 v131, v135
	v_permlane32_swap_b32_e32 v132, v136
	v_permlane32_swap_b32_e32 v133, v137
	v_lshl_add_u64 v[232:233], v[162:163], 0, v[230:231]
	global_store_dwordx4 v[232:233], v[130:133], off nt
	global_store_dwordx4 v[232:233], v[134:137], off offset:64 nt
.LBB0_356:
	s_or_b64 exec, exec, s[72:73]
	v_mov_b32_e32 v166, v154
	v_mov_b32_e32 v167, v154
	v_pk_mul_f32 v[132:133], v[166:167], v[52:53]
	v_pk_mul_f32 v[130:131], v[154:155], v[50:51]
	v_pk_mul_f32 v[136:137], v[166:167], v[20:21]
	v_pk_mul_f32 v[134:135], v[154:155], v[18:19]
	v_cvt_pk_bf16_f32 v176, v130, v131
	v_cvt_pk_bf16_f32 v177, v132, v133
	s_nop 0
	v_cvt_pk_bf16_f32 v178, v134, v135
	v_cvt_pk_bf16_f32 v179, v136, v137
	global_store_dwordx4 v[164:165], v[176:179], off offset:256
	s_and_saveexec_b64 s[72:73], s[0:1]
	s_cbranch_execz .LBB0_358
	v_permlane16_swap_b32_e32 v130, v134
	v_permlane16_swap_b32_e32 v131, v135
	v_permlane16_swap_b32_e32 v132, v136
	v_permlane16_swap_b32_e32 v133, v137
	v_permlane32_swap_b32_e32 v130, v134
	v_permlane32_swap_b32_e32 v131, v135
	v_permlane32_swap_b32_e32 v132, v136
	v_permlane32_swap_b32_e32 v133, v137
	v_lshl_add_u64 v[232:233], v[162:163], 0, v[230:231]
	global_store_dwordx4 v[232:233], v[130:133], off offset:512 nt
	global_store_dwordx4 v[232:233], v[134:137], off offset:576 nt
.LBB0_358:
	s_or_b64 exec, exec, s[72:73]
	v_add_u32_e32 v130, 0x80, v156
	v_ashrrev_i32_e32 v131, 31, v130
	v_lshlrev_b64 v[132:133], 10, v[130:131]
	v_add_u32_e32 v131, 0xffffc080, v156
	v_cndmask_b32_e32 v130, v131, v130, vcc
	v_cmp_gt_i32_e64 s[0:1], s77, v130
	v_ashrrev_i32_e32 v131, 31, v130
	s_or_b64 s[0:1], vcc, s[0:1]
	v_lshlrev_b64 v[130:131], 11, v[130:131]
	v_lshl_add_u64 v[164:165], v[160:161], 0, v[132:133]
	s_and_b64 s[0:1], s[84:85], s[0:1]
	v_lshl_add_u64 v[162:163], v[158:159], 0, v[130:131]
	v_pk_mul_f32 v[132:133], v[166:167], v[112:113]
	v_pk_mul_f32 v[130:131], v[154:155], v[110:111]
	v_pk_mul_f32 v[136:137], v[166:167], v[80:81]
	v_pk_mul_f32 v[134:135], v[154:155], v[78:79]
	v_cvt_pk_bf16_f32 v176, v130, v131
	v_cvt_pk_bf16_f32 v177, v132, v133
	s_nop 0
	v_cvt_pk_bf16_f32 v178, v134, v135
	v_cvt_pk_bf16_f32 v179, v136, v137
	global_store_dwordx4 v[164:165], v[176:179], off
	s_and_saveexec_b64 s[72:73], s[0:1]
	s_cbranch_execz .LBB0_360
	v_permlane16_swap_b32_e32 v130, v134
	v_permlane16_swap_b32_e32 v131, v135
	v_permlane16_swap_b32_e32 v132, v136
	v_permlane16_swap_b32_e32 v133, v137
	v_permlane32_swap_b32_e32 v130, v134
	v_permlane32_swap_b32_e32 v131, v135
	v_permlane32_swap_b32_e32 v132, v136
	v_permlane32_swap_b32_e32 v133, v137
	v_lshl_add_u64 v[232:233], v[162:163], 0, v[230:231]
	global_store_dwordx4 v[232:233], v[130:133], off nt
	global_store_dwordx4 v[232:233], v[134:137], off offset:64 nt
.LBB0_360:
	s_or_b64 exec, exec, s[72:73]
	v_mov_b32_e32 v166, v154
	v_mov_b32_e32 v167, v154
	v_pk_mul_f32 v[132:133], v[166:167], v[48:49]
	v_pk_mul_f32 v[130:131], v[154:155], v[46:47]
	v_pk_mul_f32 v[136:137], v[166:167], v[16:17]
	v_pk_mul_f32 v[134:135], v[154:155], v[14:15]
	v_cvt_pk_bf16_f32 v176, v130, v131
	v_cvt_pk_bf16_f32 v177, v132, v133
	s_nop 0
	v_cvt_pk_bf16_f32 v178, v134, v135
	v_cvt_pk_bf16_f32 v179, v136, v137
	global_store_dwordx4 v[164:165], v[176:179], off offset:256
	s_and_saveexec_b64 s[72:73], s[0:1]
	s_cbranch_execz .LBB0_362
	v_permlane16_swap_b32_e32 v130, v134
	v_permlane16_swap_b32_e32 v131, v135
	v_permlane16_swap_b32_e32 v132, v136
	v_permlane16_swap_b32_e32 v133, v137
	v_permlane32_swap_b32_e32 v130, v134
	v_permlane32_swap_b32_e32 v131, v135
	v_permlane32_swap_b32_e32 v132, v136
	v_permlane32_swap_b32_e32 v133, v137
	v_lshl_add_u64 v[232:233], v[162:163], 0, v[230:231]
	global_store_dwordx4 v[232:233], v[130:133], off offset:512 nt
	global_store_dwordx4 v[232:233], v[134:137], off offset:576 nt
.LBB0_362:
	s_or_b64 exec, exec, s[72:73]
	v_add_u32_e32 v130, 0x90, v156
	v_ashrrev_i32_e32 v131, 31, v130
	v_lshlrev_b64 v[132:133], 10, v[130:131]
	v_add_u32_e32 v131, 0xffffc090, v156
	v_cndmask_b32_e32 v130, v131, v130, vcc
	v_cmp_gt_i32_e64 s[0:1], s77, v130
	v_ashrrev_i32_e32 v131, 31, v130
	s_or_b64 s[0:1], vcc, s[0:1]
	v_lshlrev_b64 v[130:131], 11, v[130:131]
	v_lshl_add_u64 v[164:165], v[160:161], 0, v[132:133]
	s_and_b64 s[0:1], s[84:85], s[0:1]
	v_lshl_add_u64 v[162:163], v[158:159], 0, v[130:131]
	v_pk_mul_f32 v[132:133], v[166:167], v[108:109]
	v_pk_mul_f32 v[130:131], v[154:155], v[106:107]
	v_pk_mul_f32 v[136:137], v[166:167], v[76:77]
	v_pk_mul_f32 v[134:135], v[154:155], v[74:75]
	v_cvt_pk_bf16_f32 v176, v130, v131
	v_cvt_pk_bf16_f32 v177, v132, v133
	s_nop 0
	v_cvt_pk_bf16_f32 v178, v134, v135
	v_cvt_pk_bf16_f32 v179, v136, v137
	global_store_dwordx4 v[164:165], v[176:179], off
	s_and_saveexec_b64 s[72:73], s[0:1]
	s_cbranch_execz .LBB0_364
	v_permlane16_swap_b32_e32 v130, v134
	v_permlane16_swap_b32_e32 v131, v135
	v_permlane16_swap_b32_e32 v132, v136
	v_permlane16_swap_b32_e32 v133, v137
	v_permlane32_swap_b32_e32 v130, v134
	v_permlane32_swap_b32_e32 v131, v135
	v_permlane32_swap_b32_e32 v132, v136
	v_permlane32_swap_b32_e32 v133, v137
	v_lshl_add_u64 v[232:233], v[162:163], 0, v[230:231]
	global_store_dwordx4 v[232:233], v[130:133], off nt
	global_store_dwordx4 v[232:233], v[134:137], off offset:64 nt
.LBB0_364:
	s_or_b64 exec, exec, s[72:73]
	v_mov_b32_e32 v166, v154
	v_mov_b32_e32 v167, v154
	v_pk_mul_f32 v[132:133], v[166:167], v[44:45]
	v_pk_mul_f32 v[130:131], v[154:155], v[42:43]
	v_pk_mul_f32 v[136:137], v[166:167], v[12:13]
	v_pk_mul_f32 v[134:135], v[154:155], v[10:11]
	v_cvt_pk_bf16_f32 v176, v130, v131
	v_cvt_pk_bf16_f32 v177, v132, v133
	s_nop 0
	v_cvt_pk_bf16_f32 v178, v134, v135
	v_cvt_pk_bf16_f32 v179, v136, v137
	global_store_dwordx4 v[164:165], v[176:179], off offset:256
	s_and_saveexec_b64 s[72:73], s[0:1]
	s_cbranch_execz .LBB0_366
	v_permlane16_swap_b32_e32 v130, v134
	v_permlane16_swap_b32_e32 v131, v135
	v_permlane16_swap_b32_e32 v132, v136
	v_permlane16_swap_b32_e32 v133, v137
	v_permlane32_swap_b32_e32 v130, v134
	v_permlane32_swap_b32_e32 v131, v135
	v_permlane32_swap_b32_e32 v132, v136
	v_permlane32_swap_b32_e32 v133, v137
	v_lshl_add_u64 v[232:233], v[162:163], 0, v[230:231]
	global_store_dwordx4 v[232:233], v[130:133], off offset:512 nt
	global_store_dwordx4 v[232:233], v[134:137], off offset:576 nt
.LBB0_366:
	s_or_b64 exec, exec, s[72:73]
	v_add_u32_e32 v130, 0xa0, v156
	v_ashrrev_i32_e32 v131, 31, v130
	v_lshlrev_b64 v[132:133], 10, v[130:131]
	v_add_u32_e32 v131, 0xffffc0a0, v156
	v_cndmask_b32_e32 v130, v131, v130, vcc
	v_cmp_gt_i32_e64 s[0:1], s77, v130
	v_ashrrev_i32_e32 v131, 31, v130
	s_or_b64 s[0:1], vcc, s[0:1]
	v_lshlrev_b64 v[130:131], 11, v[130:131]
	v_lshl_add_u64 v[164:165], v[160:161], 0, v[132:133]
	s_and_b64 s[0:1], s[84:85], s[0:1]
	v_lshl_add_u64 v[162:163], v[158:159], 0, v[130:131]
	v_pk_mul_f32 v[132:133], v[166:167], v[104:105]
	v_pk_mul_f32 v[130:131], v[154:155], v[102:103]
	v_pk_mul_f32 v[136:137], v[166:167], v[72:73]
	v_pk_mul_f32 v[134:135], v[154:155], v[70:71]
	v_cvt_pk_bf16_f32 v176, v130, v131
	v_cvt_pk_bf16_f32 v177, v132, v133
	s_nop 0
	v_cvt_pk_bf16_f32 v178, v134, v135
	v_cvt_pk_bf16_f32 v179, v136, v137
	global_store_dwordx4 v[164:165], v[176:179], off
	s_and_saveexec_b64 s[72:73], s[0:1]
	s_cbranch_execz .LBB0_368
	v_permlane16_swap_b32_e32 v130, v134
	v_permlane16_swap_b32_e32 v131, v135
	v_permlane16_swap_b32_e32 v132, v136
	v_permlane16_swap_b32_e32 v133, v137
	v_permlane32_swap_b32_e32 v130, v134
	v_permlane32_swap_b32_e32 v131, v135
	v_permlane32_swap_b32_e32 v132, v136
	v_permlane32_swap_b32_e32 v133, v137
	v_lshl_add_u64 v[232:233], v[162:163], 0, v[230:231]
	global_store_dwordx4 v[232:233], v[130:133], off nt
	global_store_dwordx4 v[232:233], v[134:137], off offset:64 nt
.LBB0_368:
	s_or_b64 exec, exec, s[72:73]
	v_mov_b32_e32 v166, v154
	v_mov_b32_e32 v167, v154
	v_pk_mul_f32 v[132:133], v[166:167], v[40:41]
	v_pk_mul_f32 v[130:131], v[154:155], v[38:39]
	v_pk_mul_f32 v[136:137], v[166:167], v[8:9]
	v_pk_mul_f32 v[134:135], v[154:155], v[6:7]
	v_cvt_pk_bf16_f32 v176, v130, v131
	v_cvt_pk_bf16_f32 v177, v132, v133
	s_nop 0
	v_cvt_pk_bf16_f32 v178, v134, v135
	v_cvt_pk_bf16_f32 v179, v136, v137
	global_store_dwordx4 v[164:165], v[176:179], off offset:256
	s_and_saveexec_b64 s[72:73], s[0:1]
	s_cbranch_execz .LBB0_370
	v_permlane16_swap_b32_e32 v130, v134
	v_permlane16_swap_b32_e32 v131, v135
	v_permlane16_swap_b32_e32 v132, v136
	v_permlane16_swap_b32_e32 v133, v137
	v_permlane32_swap_b32_e32 v130, v134
	v_permlane32_swap_b32_e32 v131, v135
	v_permlane32_swap_b32_e32 v132, v136
	v_permlane32_swap_b32_e32 v133, v137
	v_lshl_add_u64 v[232:233], v[162:163], 0, v[230:231]
	global_store_dwordx4 v[232:233], v[130:133], off offset:512 nt
	global_store_dwordx4 v[232:233], v[134:137], off offset:576 nt
.LBB0_370:
	s_or_b64 exec, exec, s[72:73]
	v_add_u32_e32 v130, 0xb0, v156
	v_ashrrev_i32_e32 v131, 31, v130
	v_lshlrev_b64 v[132:133], 10, v[130:131]
	v_add_u32_e32 v131, 0xffffc0b0, v156
	v_cndmask_b32_e32 v130, v131, v130, vcc
	v_cmp_gt_i32_e64 s[0:1], s77, v130
	v_ashrrev_i32_e32 v131, 31, v130
	s_or_b64 s[0:1], vcc, s[0:1]
	v_lshlrev_b64 v[130:131], 11, v[130:131]
	v_lshl_add_u64 v[160:161], v[160:161], 0, v[132:133]
	s_and_b64 s[0:1], s[84:85], s[0:1]
	v_lshl_add_u64 v[156:157], v[158:159], 0, v[130:131]
	v_pk_mul_f32 v[132:133], v[166:167], v[100:101]
	v_pk_mul_f32 v[130:131], v[154:155], v[98:99]
	v_pk_mul_f32 v[136:137], v[166:167], v[68:69]
	v_pk_mul_f32 v[134:135], v[154:155], v[66:67]
	v_cvt_pk_bf16_f32 v162, v130, v131
	v_cvt_pk_bf16_f32 v163, v132, v133
	s_nop 0
	v_cvt_pk_bf16_f32 v164, v134, v135
	v_cvt_pk_bf16_f32 v165, v136, v137
	global_store_dwordx4 v[160:161], v[162:165], off
	s_and_saveexec_b64 s[72:73], s[0:1]
	s_cbranch_execz .LBB0_372
	v_permlane16_swap_b32_e32 v130, v134
	v_permlane16_swap_b32_e32 v131, v135
	v_permlane16_swap_b32_e32 v132, v136
	v_permlane16_swap_b32_e32 v133, v137
	v_permlane32_swap_b32_e32 v130, v134
	v_permlane32_swap_b32_e32 v131, v135
	v_permlane32_swap_b32_e32 v132, v136
	v_permlane32_swap_b32_e32 v133, v137
	v_lshl_add_u64 v[232:233], v[156:157], 0, v[230:231]
	global_store_dwordx4 v[232:233], v[130:133], off nt
	global_store_dwordx4 v[232:233], v[134:137], off offset:64 nt
.LBB0_372:
	s_or_b64 exec, exec, s[72:73]
	s_nop 0
	v_mov_b32_e32 v134, v154
	v_mov_b32_e32 v135, v154
	v_pk_mul_f32 v[132:133], v[134:135], v[36:37]
	v_pk_mul_f32 v[130:131], v[154:155], v[34:35]
	v_pk_mul_f32 v[136:137], v[134:135], v[4:5]
	v_pk_mul_f32 v[134:135], v[154:155], v[2:3]
	v_cvt_pk_bf16_f32 v162, v130, v131
	v_cvt_pk_bf16_f32 v163, v132, v133
	s_nop 0
	v_cvt_pk_bf16_f32 v164, v134, v135
	v_cvt_pk_bf16_f32 v165, v136, v137
	global_store_dwordx4 v[160:161], v[162:165], off offset:256
	s_and_saveexec_b64 s[72:73], s[0:1]
	s_cbranch_execz .LBB0_374
	v_permlane16_swap_b32_e32 v130, v134
	v_permlane16_swap_b32_e32 v131, v135
	v_permlane16_swap_b32_e32 v132, v136
	v_permlane16_swap_b32_e32 v133, v137
	v_permlane32_swap_b32_e32 v130, v134
	v_permlane32_swap_b32_e32 v131, v135
	v_permlane32_swap_b32_e32 v132, v136
	v_permlane32_swap_b32_e32 v133, v137
	v_lshl_add_u64 v[232:233], v[156:157], 0, v[230:231]
	global_store_dwordx4 v[232:233], v[130:133], off offset:512 nt
	global_store_dwordx4 v[232:233], v[134:137], off offset:576 nt

.LBB0_1253:
	v_lshl_add_u64 v[0:1], s[6:7], 0, v[16:17]
	v_add_co_u32_e32 v38, vcc, 0x10000000, v0
	s_nop 1
	v_addc_co_u32_e32 v39, vcc, 0, v1, vcc
	global_load_dwordx4 v[40:43], v[38:39], off
	global_load_dwordx4 v[44:47], v[38:39], off offset:1024
	global_load_dwordx4 v[48:51], v[38:39], off offset:2048
	global_load_dwordx4 v[52:55], v[38:39], off offset:3072
	global_load_dwordx4 v[56:59], v[18:19], off
	global_load_dwordx4 v[60:63], v[18:19], off offset:1024
	global_load_dwordx4 v[64:67], v[18:19], off offset:2048
	global_load_dwordx4 v[68:71], v[18:19], off offset:3072
	global_load_dwordx4 v[72:75], v[20:21], off
	global_load_dwordx4 v[76:79], v[20:21], off offset:1024
	global_load_dwordx4 v[80:83], v[20:21], off offset:2048
	global_load_dwordx4 v[84:87], v[20:21], off offset:3072
	v_lshl_add_u64 v[38:39], s[2:3], 0, v[16:17]
	v_add_co_u32_e32 v38, vcc, s9, v38
	s_nop 1
	v_addc_co_u32_e32 v39, vcc, 0, v39, vcc
	s_waitcnt vmcnt(8)
	v_add_f32_e32 v4, v40, v41
	v_add_f32_e32 v5, v42, v43
	v_add_f32_e32 v2, v4, v5
	v_add_f32_e32 v4, v44, v45
	v_add_f32_e32 v5, v46, v47
	v_add_f32_e32 v4, v4, v5
	v_add_f32_e32 v2, v2, v4
	v_add_f32_e32 v4, v48, v49
	v_add_f32_e32 v5, v50, v51
	v_add_f32_e32 v4, v4, v5
	v_add_f32_e32 v2, v2, v4
	v_add_f32_e32 v4, v52, v53
	v_add_f32_e32 v5, v54, v55
	v_add_f32_e32 v4, v4, v5
	v_add_f32_e32 v2, v2, v4
	ds_bpermute_b32 v4, v22, v2
	s_waitcnt lgkmcnt(0)
	v_add_f32_e32 v2, v2, v4
	ds_bpermute_b32 v4, v23, v2
	s_waitcnt lgkmcnt(0)
	v_add_f32_e32 v2, v2, v4
	ds_bpermute_b32 v4, v24, v2
	s_waitcnt lgkmcnt(0)
	v_add_f32_e32 v2, v2, v4
	ds_bpermute_b32 v4, v25, v2
	s_waitcnt lgkmcnt(0)
	v_add_f32_e32 v2, v2, v4
	ds_bpermute_b32 v4, v26, v2
	s_waitcnt lgkmcnt(0)
	v_add_f32_e32 v2, v2, v4
	ds_bpermute_b32 v4, v27, v2
	s_waitcnt lgkmcnt(0)
	v_add_f32_e32 v2, v2, v4
	v_fmac_f32_e32 v40, 0xba800000, v2
	v_fmac_f32_e32 v41, 0xba800000, v2
	v_fmac_f32_e32 v42, 0xba800000, v2
	v_fmac_f32_e32 v43, 0xba800000, v2
	v_fmac_f32_e32 v44, 0xba800000, v2
	v_fmac_f32_e32 v45, 0xba800000, v2
	v_fmac_f32_e32 v46, 0xba800000, v2
	v_fmac_f32_e32 v47, 0xba800000, v2
	v_fmac_f32_e32 v48, 0xba800000, v2
	v_fmac_f32_e32 v49, 0xba800000, v2
	v_fmac_f32_e32 v50, 0xba800000, v2
	v_fmac_f32_e32 v51, 0xba800000, v2
	v_fmac_f32_e32 v52, 0xba800000, v2
	v_fmac_f32_e32 v53, 0xba800000, v2
	v_fmac_f32_e32 v54, 0xba800000, v2
	v_fmac_f32_e32 v55, 0xba800000, v2
	v_mul_f32_e32 v4, v40, v40
	v_fmac_f32_e32 v4, v41, v41
	v_mul_f32_e32 v5, v42, v42
	v_fmac_f32_e32 v5, v43, v43
	v_add_f32_e32 v2, v4, v5
	v_mul_f32_e32 v4, v44, v44
	v_fmac_f32_e32 v4, v45, v45
	v_mul_f32_e32 v5, v46, v46
	v_fmac_f32_e32 v5, v47, v47
	v_add_f32_e32 v4, v4, v5
	v_add_f32_e32 v2, v2, v4
	v_mul_f32_e32 v4, v48, v48
	v_fmac_f32_e32 v4, v49, v49
	v_mul_f32_e32 v5, v50, v50
	v_fmac_f32_e32 v5, v51, v51
	v_add_f32_e32 v4, v4, v5
	v_add_f32_e32 v2, v2, v4
	v_mul_f32_e32 v4, v52, v52
	v_fmac_f32_e32 v4, v53, v53
	v_mul_f32_e32 v5, v54, v54
	v_fmac_f32_e32 v5, v55, v55
	v_add_f32_e32 v4, v4, v5
	v_add_f32_e32 v2, v2, v4
	ds_bpermute_b32 v4, v22, v2
	s_waitcnt lgkmcnt(0)
	v_add_f32_e32 v2, v2, v4
	ds_bpermute_b32 v4, v23, v2
	s_waitcnt lgkmcnt(0)
	v_add_f32_e32 v2, v2, v4
	ds_bpermute_b32 v4, v24, v2
	s_waitcnt lgkmcnt(0)
	v_add_f32_e32 v2, v2, v4
	ds_bpermute_b32 v4, v25, v2
	s_waitcnt lgkmcnt(0)
	v_add_f32_e32 v2, v2, v4
	ds_bpermute_b32 v4, v26, v2
	s_waitcnt lgkmcnt(0)
	v_add_f32_e32 v2, v2, v4
	ds_bpermute_b32 v4, v27, v2
	s_waitcnt lgkmcnt(0)
	v_add_f32_e32 v2, v2, v4
	v_mov_b32_e32 v7, v28
	v_fmac_f32_e32 v7, 0x3a800000, v2
	v_mul_f32_e32 v6, 0x4f800000, v7
	v_cmp_gt_f32_e32 vcc, s8, v7
	s_nop 1
	v_cndmask_b32_e32 v6, v7, v6, vcc
	v_sqrt_f32_e32 v7, v6
	s_nop 0
	v_add_u32_e32 v8, -1, v7
	v_fma_f32 v9, -v8, v7, v6
	v_cmp_ge_f32_e64 s[0:1], 0, v9
	v_add_u32_e32 v9, 1, v7
	s_nop 0
	v_cndmask_b32_e64 v8, v7, v8, s[0:1]
	v_fma_f32 v7, -v9, v7, v6
	v_cmp_lt_f32_e64 s[0:1], 0, v7
	s_nop 1
	v_cndmask_b32_e64 v7, v8, v9, s[0:1]
	v_mul_f32_e32 v8, 0x37800000, v7
	v_cndmask_b32_e32 v7, v7, v8, vcc
	v_cmp_class_f32_e32 vcc, v6, v29
	s_nop 1
	v_cndmask_b32_e32 v6, v7, v6, vcc
	v_div_scale_f32 v7, s[0:1], v6, v6, 1.0
	v_rcp_f32_e32 v8, v7
	s_nop 0
	v_fma_f32 v9, -v7, v8, 1.0
	v_fmac_f32_e32 v8, v9, v8
	v_div_scale_f32 v9, vcc, 1.0, v6, 1.0
	v_mul_f32_e32 v10, v9, v8
	v_fma_f32 v11, -v7, v10, v9
	v_fmac_f32_e32 v10, v11, v8
	v_fma_f32 v7, -v7, v10, v9
	v_div_fmas_f32 v7, v7, v8, v10
	v_div_fixup_f32 v3, v7, v6, 1.0
	s_waitcnt vmcnt(0)
	v_mul_f32_e32 v40, v40, v3
	v_mul_f32_e32 v41, v41, v3
	v_mul_f32_e32 v42, v42, v3
	v_mul_f32_e32 v43, v43, v3
	v_fma_f32 v40, v40, v56, v72
	v_fma_f32 v41, v41, v57, v73
	v_fma_f32 v42, v42, v58, v74
	v_fma_f32 v43, v43, v59, v75
	global_store_dwordx4 v[38:39], v[40:43], off
	v_mul_f32_e32 v44, v44, v3
	v_mul_f32_e32 v45, v45, v3
	v_mul_f32_e32 v46, v46, v3
	v_mul_f32_e32 v47, v47, v3
	v_fma_f32 v44, v44, v60, v76
	v_fma_f32 v45, v45, v61, v77
	v_fma_f32 v46, v46, v62, v78
	v_fma_f32 v47, v47, v63, v79
	global_store_dwordx4 v[38:39], v[44:47], off offset:1024
	v_mul_f32_e32 v48, v48, v3
	v_mul_f32_e32 v49, v49, v3
	v_mul_f32_e32 v50, v50, v3
	v_mul_f32_e32 v51, v51, v3
	v_fma_f32 v48, v48, v64, v80
	v_fma_f32 v49, v49, v65, v81
	v_fma_f32 v50, v50, v66, v82
	v_fma_f32 v51, v51, v67, v83
	global_store_dwordx4 v[38:39], v[48:51], off offset:2048
	v_mul_f32_e32 v52, v52, v3
	v_mul_f32_e32 v53, v53, v3
	v_mul_f32_e32 v54, v54, v3
	v_mul_f32_e32 v55, v55, v3
	v_fma_f32 v52, v52, v68, v84
	v_fma_f32 v53, v53, v69, v85
	v_fma_f32 v54, v54, v70, v86
	v_fma_f32 v55, v55, v71, v87
	global_store_dwordx4 v[38:39], v[52:55], off offset:3072
